# GEMM1 epilogue: bf16 GLU/gate/q/k outputs staged through a wave-private LDS image so each store writes full 128B row segments (was 16B per lane into 64 rows)
# speedup vs baseline: 1.0127x; 1.0127x over previous
.LBB0_202:
	s_cmp_lt_i32 s64, 3
	s_cselect_b64 s[16:17], -1, 0
	s_and_b64 s[0:1], s[16:17], s[0:1]
	s_xor_b64 s[0:1], s[0:1], -1
	s_cmpk_gt_i32 s2, 0x6ff
	s_cselect_b64 s[4:5], -1, 0
	s_or_b64 s[0:1], s[0:1], s[4:5]
	s_and_b64 vcc, exec, s[0:1]
	v_mbcnt_lo_u32_b32 v213, -1, 0
	s_cbranch_vccnz .LBB0_386
	v_and_b32_e32 v176, 63, v212
	v_and_b32_e32 v177, 31, v212
	v_bfe_u32 v178, v212, 5, 1
	v_lshrrev_b32_e32 v179, 6, v212
	v_mul_u32_u24_e32 v179, 0x1200, v179
	v_add_u32_e32 v179, 0x12000, v179
	v_mul_u32_u24_e32 v180, 0x90, v177
	v_add_u32_e32 v180, v180, v179
	v_lshl_add_u32 v202, v178, 6, v180
	v_lshl_add_u32 v203, v178, 5, v180
	v_lshrrev_b32_e32 v181, 3, v176
	v_and_b32_e32 v182, 7, v176
	v_mul_u32_u24_e32 v183, 0x240, v181
	v_add_u32_e32 v183, v183, v179
	v_lshl_add_u32 v204, v182, 4, v183
	v_lshrrev_b32_e32 v184, 2, v176
	v_and_b32_e32 v185, 3, v176
	v_mul_u32_u24_e32 v186, 0x120, v184
	v_add_u32_e32 v186, v186, v179
	v_lshl_add_u32 v205, v185, 4, v186
	v_lshlrev_b32_e32 v187, 2, v181
	v_sub_u32_e32 v187, v187, v177
	v_lshlrev_b32_e32 v188, 4, v182
	v_lshlrev_b32_e32 v189, 6, v178
	v_sub_u32_e32 v188, v188, v189
	v_lshl_add_u32 v206, v187, 10, v188
	v_ashrrev_i32_e32 v207, 31, v206
	v_lshl_add_u32 v208, v187, 7, v188
	v_ashrrev_i32_e32 v209, 31, v208
	v_lshlrev_b32_e32 v190, 1, v184
	v_sub_u32_e32 v190, v190, v177
	v_lshlrev_b32_e32 v191, 4, v185
	v_lshlrev_b32_e32 v189, 5, v178
	v_sub_u32_e32 v191, v191, v189
	v_lshl_add_u32 v210, v190, 10, v191
	v_ashrrev_i32_e32 v211, 31, v210
	s_and_b32 s0, s62, 7
	s_cmp_lg_u32 s0, 0
	s_cselect_b64 s[0:1], -1, 0
	s_ashr_i32 s44, s62, 3
	s_add_u32 s45, s96, 0x20000
	s_addc_u32 s46, s97, 0
	s_add_u32 s47, s96, 0x13a0000
	s_addc_u32 s48, s97, 0
	s_add_u32 s18, s96, 0xd3a4000
	s_addc_u32 s19, s97, 0
	s_add_u32 s20, s96, 0x73a0000
	s_addc_u32 s21, s97, 0
	s_add_u32 s22, s96, 0x8ba0000
	s_addc_u32 s23, s97, 0
	s_add_u32 s24, s96, 0xa3a0000
	s_addc_u32 s25, s97, 0
	s_add_u32 s26, s74, 0x7000000
	s_addc_u32 s27, s75, 0
	s_add_u32 s28, s74, 0x6000000
	s_addc_u32 s29, s75, 0
	s_abs_i32 s49, s62
	v_cvt_f32_u32_e32 v2, s49
	s_sub_i32 s3, 0, s49
	v_cndmask_b32_e64 v3, 0, 1, s[0:1]
	s_mov_b64 s[72:73], s[60:61]
	v_rcp_iflag_f32_e32 v2, v2
	v_mov_b32_e32 v99, 0
	s_movk_i32 s50, 0x90
	v_cmp_ne_u32_e64 s[0:1], 1, v3
	v_mul_f32_e32 v2, 0x4f7ffffe, v2
	v_cvt_u32_f32_e32 v2, v2
	s_ashr_i32 s51, s62, 31
	s_sub_i32 s52, 0, s62
	s_mov_b32 s54, 0x20000
	v_readfirstlane_b32 s4, v2
	s_mul_i32 s3, s3, s4
	s_mul_hi_u32 s3, s4, s3
	s_add_i32 s53, s4, s3
	s_mov_b32 s55, 0x40000
	s_movk_i32 s56, 0x110
	s_movk_i32 s57, 0x2000
	v_mov_b32_e32 v124, 0x358637bd
	s_mov_b32 s58, 0x800000
	s_movk_i32 s59, 0x1fe0
	s_movk_i32 s60, 0x1fc0
	v_mov_b32_e32 v125, 0x60
	v_mov_b32_e32 v126, 0x440
	v_mov_b32_e32 v127, 0x880
	v_mov_b32_e32 v128, 0xfffffa00
	v_mov_b32_e32 v129, 0xfffff800
	v_mov_b32_e32 v130, 0x3e38aa3b
	v_mbcnt_hi_u32_b32 v132, -1, v213
	v_mov_b32_e32 v133, 0xbb9e800
	v_mov_b32_e32 v134, 0x5b9f800
	s_mov_b32 s61, s2
	s_branch .LBB0_205

.LBB0_208:
	s_lshl_b32 s4, s8, 8
	s_ashr_i32 s5, s4, 31
	v_mov_b32_e32 v58, v212
	s_lshl_b64 s[10:11], s[4:5], 11
	s_add_u32 s10, s45, s10
	v_ashrrev_i32_e32 v30, 3, v58
	v_ashrrev_i32_e32 v31, 31, v30
	s_addc_u32 s11, s46, s11
	v_lshlrev_b64 v[2:3], 11, v[30:31]
	v_lshlrev_b32_e32 v6, 4, v58
	v_lshl_add_u64 v[4:5], s[10:11], 0, v[2:3]
	v_and_b32_e32 v98, 0x70, v6
	v_lshl_add_u64 v[102:103], v[4:5], 0, v[98:99]
	s_mul_i32 s6, s9, 0xc0
	v_add_co_u32_e32 v106, vcc, s54, v102
	s_ashr_i32 s7, s6, 31
	s_nop 0
	v_addc_co_u32_e32 v107, vcc, 0, v103, vcc
	s_lshl_b64 s[12:13], s[6:7], 11
	v_add_co_u32_e32 v108, vcc, s55, v102
	s_add_u32 s12, s47, s12
	s_nop 0
	v_addc_co_u32_e32 v109, vcc, 0, v103, vcc
	s_mov_b32 s3, 0x60000
	s_addc_u32 s13, s48, s13
	v_add_co_u32_e32 v110, vcc, s3, v102
	v_lshl_add_u64 v[2:3], s[12:13], 0, v[2:3]
	s_nop 0
	v_addc_co_u32_e32 v111, vcc, 0, v103, vcc
	v_lshl_add_u64 v[104:105], v[2:3], 0, v[98:99]
	global_load_dwordx4 v[2:5], v[102:103], off
	global_load_dwordx4 v[6:9], v[106:107], off
	global_load_dwordx4 v[10:13], v[108:109], off
	global_load_dwordx4 v[14:17], v[110:111], off
	global_load_dwordx4 v[18:21], v[104:105], off
	v_add_co_u32_e32 v112, vcc, s54, v104
	v_mad_u64_u32 v[114:115], s[10:11], v30, s50, v[98:99]
	s_nop 0
	v_addc_co_u32_e32 v113, vcc, 0, v105, vcc
	v_add_co_u32_e32 v116, vcc, s55, v104
	global_load_dwordx4 v[22:25], v[112:113], off
	s_nop 0
	v_addc_co_u32_e32 v117, vcc, 0, v105, vcc
	global_load_dwordx4 v[26:29], v[116:117], off
	global_load_dwordx4 v[30:33], v[102:103], off offset:128
	global_load_dwordx4 v[34:37], v[106:107], off offset:128
	global_load_dwordx4 v[38:41], v[108:109], off offset:128
	global_load_dwordx4 v[42:45], v[110:111], off offset:128
	global_load_dwordx4 v[46:49], v[104:105], off offset:128
	global_load_dwordx4 v[50:53], v[112:113], off offset:128
	global_load_dwordx4 v[54:57], v[116:117], off offset:128
	s_mov_b32 s3, 0xfffffc0
	v_add_u32_e32 v119, 0x12000, v114
	s_waitcnt vmcnt(13)
	ds_write_b128 v114, v[2:5]
	s_waitcnt vmcnt(12)
	ds_write_b128 v114, v[6:9] offset:9216
	s_waitcnt vmcnt(11)
	ds_write_b128 v114, v[10:13] offset:18432
	s_waitcnt vmcnt(10)
	ds_write_b128 v114, v[14:17] offset:27648
	s_waitcnt vmcnt(9)
	ds_write_b128 v114, v[18:21] offset:36864
	s_waitcnt vmcnt(8)
	ds_write_b128 v114, v[22:25] offset:46080
	s_waitcnt vmcnt(7)
	ds_write_b128 v114, v[26:29] offset:55296
	s_waitcnt lgkmcnt(0)
	s_barrier
	global_load_dwordx4 v[120:123], v[106:107], off offset:256
	global_load_dwordx4 v[136:139], v[108:109], off offset:256
	global_load_dwordx4 v[140:143], v[102:103], off offset:256
	global_load_dwordx4 v[144:147], v[104:105], off offset:256
	global_load_dwordx4 v[148:151], v[110:111], off offset:256
	global_load_dwordx4 v[152:155], v[112:113], off offset:256
	global_load_dwordx4 v[156:159], v[116:117], off offset:256
	v_and_b32_e32 v3, 31, v58
	v_lshrrev_b32_e32 v2, 1, v58
	v_and_or_b32 v4, v2, s3, v3
	v_bfe_i32 v5, v58, 6, 1
	s_movk_i32 s3, 0x60
	v_and_b32_e32 v2, 16, v2
	v_and_or_b32 v3, v5, s3, v3
	v_mad_u32_u24 v115, v3, s50, v2
	v_add_u32_e32 v98, 0x12000, v115
	s_waitcnt vmcnt(13)
	ds_write_b128 v119, v[30:33]
	s_waitcnt vmcnt(12)
	ds_write_b128 v119, v[34:37] offset:9216
	s_waitcnt vmcnt(11)
	ds_write_b128 v119, v[38:41] offset:18432
	s_waitcnt vmcnt(10)
	ds_write_b128 v119, v[42:45] offset:27648
	s_waitcnt vmcnt(9)
	ds_write_b128 v119, v[46:49] offset:36864
	s_waitcnt vmcnt(8)
	ds_write_b128 v119, v[50:53] offset:46080
	s_waitcnt vmcnt(7)
	ds_write_b128 v119, v[54:57] offset:55296
	v_mad_u64_u32 v[100:101], s[10:11], v4, s50, v[2:3]
	ds_read_b128 v[18:21], v115 offset:36864
	ds_read_b128 v[162:165], v115 offset:36896
	ds_read_b128 v[22:25], v115 offset:41472
	ds_read_b128 v[166:169], v115 offset:41504
	ds_read_b128 v[26:29], v115 offset:46080
	ds_read_b128 v[170:173], v115 offset:46112
	ds_read_b128 v[2:5], v100
	ds_read_b128 v[174:177], v100 offset:32
	ds_read_b128 v[30:33], v100 offset:4608
	ds_read_b128 v[178:181], v100 offset:4640
	s_setprio 1
	s_waitcnt lgkmcnt(3)
	v_mfma_f32_32x32x16_bf16 v[82:97], v[2:5], v[18:21], 0
	v_mfma_f32_32x32x16_bf16 v[50:65], v[2:5], v[22:25], 0
	v_mfma_f32_32x32x16_bf16 v[2:17], v[2:5], v[26:29], 0
	s_waitcnt lgkmcnt(1)
	v_mfma_f32_32x32x16_bf16 v[66:81], v[30:33], v[18:21], 0
	v_mfma_f32_32x32x16_bf16 v[34:49], v[30:33], v[22:25], 0
	v_mfma_f32_32x32x16_bf16 v[18:33], v[30:33], v[26:29], 0
	s_setprio 0
	ds_read_b128 v[182:185], v115 offset:36928
	ds_read_b128 v[186:189], v115 offset:41536
	ds_read_b128 v[190:193], v115 offset:46144
	ds_read_b128 v[194:197], v100 offset:64
	ds_read_b128 v[198:201], v100 offset:4672
	s_setprio 1
	v_mfma_f32_32x32x16_bf16 v[82:97], v[174:177], v[162:165], v[82:97]
	v_mfma_f32_32x32x16_bf16 v[50:65], v[174:177], v[166:169], v[50:65]
	v_mfma_f32_32x32x16_bf16 v[2:17], v[174:177], v[170:173], v[2:17]
	s_waitcnt lgkmcnt(5)
	v_mfma_f32_32x32x16_bf16 v[66:81], v[178:181], v[162:165], v[66:81]
	v_mfma_f32_32x32x16_bf16 v[34:49], v[178:181], v[166:169], v[34:49]
	v_mfma_f32_32x32x16_bf16 v[18:33], v[178:181], v[170:173], v[18:33]
	s_setprio 0
	ds_read_b128 v[162:165], v115 offset:36960
	ds_read_b128 v[166:169], v115 offset:41568
	ds_read_b128 v[170:173], v115 offset:46176
	ds_read_b128 v[174:177], v100 offset:96
	ds_read_b128 v[178:181], v100 offset:4704
	s_setprio 1
	s_waitcnt lgkmcnt(6)
	v_mfma_f32_32x32x16_bf16 v[82:97], v[194:197], v[182:185], v[82:97]
	v_mfma_f32_32x32x16_bf16 v[50:65], v[194:197], v[186:189], v[50:65]
	v_mfma_f32_32x32x16_bf16 v[2:17], v[194:197], v[190:193], v[2:17]
	s_waitcnt lgkmcnt(5)
	v_mfma_f32_32x32x16_bf16 v[66:81], v[198:201], v[182:185], v[66:81]
	v_mfma_f32_32x32x16_bf16 v[34:49], v[198:201], v[186:189], v[34:49]
	v_mfma_f32_32x32x16_bf16 v[18:33], v[198:201], v[190:193], v[18:33]
	s_setprio 0
	s_setprio 1
	s_waitcnt lgkmcnt(1)
	v_mfma_f32_32x32x16_bf16 v[82:97], v[174:177], v[162:165], v[82:97]
	v_mfma_f32_32x32x16_bf16 v[50:65], v[174:177], v[166:169], v[50:65]
	v_mfma_f32_32x32x16_bf16 v[2:17], v[174:177], v[170:173], v[2:17]
	s_waitcnt lgkmcnt(0)
	v_mfma_f32_32x32x16_bf16 v[66:81], v[178:181], v[162:165], v[66:81]
	v_mfma_f32_32x32x16_bf16 v[34:49], v[178:181], v[166:169], v[34:49]
	v_mfma_f32_32x32x16_bf16 v[18:33], v[178:181], v[170:173], v[18:33]
	s_setprio 0
	s_barrier
	global_load_dwordx4 v[162:165], v[106:107], off offset:384
	global_load_dwordx4 v[166:169], v[108:109], off offset:384
	global_load_dwordx4 v[170:173], v[102:103], off offset:384
	global_load_dwordx4 v[174:177], v[104:105], off offset:384
	global_load_dwordx4 v[178:181], v[110:111], off offset:384
	global_load_dwordx4 v[182:185], v[112:113], off offset:384
	global_load_dwordx4 v[186:189], v[116:117], off offset:384
	s_waitcnt vmcnt(11)
	ds_write_b128 v114, v[140:143]
	ds_write_b128 v114, v[120:123] offset:9216
	ds_write_b128 v114, v[136:139] offset:18432
	s_waitcnt vmcnt(9)
	ds_write_b128 v114, v[148:151] offset:27648
	ds_write_b128 v114, v[144:147] offset:36864
	s_waitcnt vmcnt(8)
	ds_write_b128 v114, v[152:155] offset:46080
	s_waitcnt vmcnt(7)
	ds_write_b128 v114, v[156:159] offset:55296
	v_add_u32_e32 v101, 0x12000, v100
	ds_read_b128 v[120:123], v98 offset:36864
	ds_read_b128 v[136:139], v98 offset:36896
	ds_read_b128 v[140:143], v98 offset:41472
	ds_read_b128 v[144:147], v98 offset:41504
	ds_read_b128 v[148:151], v98 offset:46080
	ds_read_b128 v[152:155], v98 offset:46112
	ds_read_b128 v[156:159], v101
	ds_read_b128 v[190:193], v101 offset:32
	ds_read_b128 v[194:197], v101 offset:4608
	ds_read_b128 v[198:201], v101 offset:4640
	s_setprio 1
	s_waitcnt lgkmcnt(3)
	v_mfma_f32_32x32x16_bf16 v[82:97], v[156:159], v[120:123], v[82:97]
	v_mfma_f32_32x32x16_bf16 v[50:65], v[156:159], v[140:143], v[50:65]
	v_mfma_f32_32x32x16_bf16 v[2:17], v[156:159], v[148:151], v[2:17]
	s_waitcnt lgkmcnt(1)
	v_mfma_f32_32x32x16_bf16 v[66:81], v[194:197], v[120:123], v[66:81]
	v_mfma_f32_32x32x16_bf16 v[34:49], v[194:197], v[140:143], v[34:49]
	v_mfma_f32_32x32x16_bf16 v[18:33], v[194:197], v[148:151], v[18:33]
	s_setprio 0
	ds_read_b128 v[120:123], v98 offset:36928
	ds_read_b128 v[140:143], v98 offset:41536
	ds_read_b128 v[148:151], v98 offset:46144
	ds_read_b128 v[156:159], v101 offset:64
	ds_read_b128 v[194:197], v101 offset:4672
	s_setprio 1
	v_mfma_f32_32x32x16_bf16 v[82:97], v[190:193], v[136:139], v[82:97]
	v_mfma_f32_32x32x16_bf16 v[50:65], v[190:193], v[144:147], v[50:65]
	v_mfma_f32_32x32x16_bf16 v[2:17], v[190:193], v[152:155], v[2:17]
	s_waitcnt lgkmcnt(5)
	v_mfma_f32_32x32x16_bf16 v[66:81], v[198:201], v[136:139], v[66:81]
	v_mfma_f32_32x32x16_bf16 v[34:49], v[198:201], v[144:147], v[34:49]
	v_mfma_f32_32x32x16_bf16 v[18:33], v[198:201], v[152:155], v[18:33]
	s_setprio 0
	ds_read_b128 v[136:139], v98 offset:36960
	ds_read_b128 v[144:147], v98 offset:41568
	ds_read_b128 v[152:155], v98 offset:46176
	ds_read_b128 v[190:193], v101 offset:96
	ds_read_b128 v[198:201], v101 offset:4704
	s_setprio 1
	s_waitcnt lgkmcnt(6)
	v_mfma_f32_32x32x16_bf16 v[82:97], v[156:159], v[120:123], v[82:97]
	v_mfma_f32_32x32x16_bf16 v[50:65], v[156:159], v[140:143], v[50:65]
	v_mfma_f32_32x32x16_bf16 v[2:17], v[156:159], v[148:151], v[2:17]
	s_waitcnt lgkmcnt(5)
	v_mfma_f32_32x32x16_bf16 v[66:81], v[194:197], v[120:123], v[66:81]
	v_mfma_f32_32x32x16_bf16 v[34:49], v[194:197], v[140:143], v[34:49]
	v_mfma_f32_32x32x16_bf16 v[18:33], v[194:197], v[148:151], v[18:33]
	s_setprio 0
	s_setprio 1
	s_waitcnt lgkmcnt(1)
	v_mfma_f32_32x32x16_bf16 v[82:97], v[190:193], v[136:139], v[82:97]
	v_mfma_f32_32x32x16_bf16 v[50:65], v[190:193], v[144:147], v[50:65]
	v_mfma_f32_32x32x16_bf16 v[2:17], v[190:193], v[152:155], v[2:17]
	s_waitcnt lgkmcnt(0)
	v_mfma_f32_32x32x16_bf16 v[66:81], v[198:201], v[136:139], v[66:81]
	v_mfma_f32_32x32x16_bf16 v[34:49], v[198:201], v[144:147], v[34:49]
	v_mfma_f32_32x32x16_bf16 v[18:33], v[198:201], v[152:155], v[18:33]
	s_setprio 0
	s_barrier
	global_load_dwordx4 v[120:123], v[106:107], off offset:512
	global_load_dwordx4 v[136:139], v[108:109], off offset:512
	global_load_dwordx4 v[140:143], v[102:103], off offset:512
	global_load_dwordx4 v[144:147], v[104:105], off offset:512
	global_load_dwordx4 v[148:151], v[110:111], off offset:512
	global_load_dwordx4 v[152:155], v[112:113], off offset:512
	global_load_dwordx4 v[156:159], v[116:117], off offset:512
	s_waitcnt vmcnt(11)
	ds_write_b128 v119, v[170:173]
	ds_write_b128 v119, v[162:165] offset:9216
	ds_write_b128 v119, v[166:169] offset:18432
	s_waitcnt vmcnt(9)
	ds_write_b128 v119, v[178:181] offset:27648
	ds_write_b128 v119, v[174:177] offset:36864
	s_waitcnt vmcnt(8)
	ds_write_b128 v119, v[182:185] offset:46080
	s_waitcnt vmcnt(7)
	ds_write_b128 v119, v[186:189] offset:55296
	ds_read_b128 v[162:165], v115 offset:36864
	ds_read_b128 v[166:169], v115 offset:36896
	ds_read_b128 v[170:173], v115 offset:41472
	ds_read_b128 v[174:177], v115 offset:41504
	ds_read_b128 v[178:181], v115 offset:46080
	ds_read_b128 v[182:185], v115 offset:46112
	ds_read_b128 v[186:189], v100
	ds_read_b128 v[190:193], v100 offset:32
	ds_read_b128 v[194:197], v100 offset:4608
	ds_read_b128 v[198:201], v100 offset:4640
	s_setprio 1
	s_waitcnt lgkmcnt(3)
	v_mfma_f32_32x32x16_bf16 v[82:97], v[186:189], v[162:165], v[82:97]
	v_mfma_f32_32x32x16_bf16 v[50:65], v[186:189], v[170:173], v[50:65]
	v_mfma_f32_32x32x16_bf16 v[2:17], v[186:189], v[178:181], v[2:17]
	s_waitcnt lgkmcnt(1)
	v_mfma_f32_32x32x16_bf16 v[66:81], v[194:197], v[162:165], v[66:81]
	v_mfma_f32_32x32x16_bf16 v[34:49], v[194:197], v[170:173], v[34:49]
	v_mfma_f32_32x32x16_bf16 v[18:33], v[194:197], v[178:181], v[18:33]
	s_setprio 0
	ds_read_b128 v[162:165], v115 offset:36928
	ds_read_b128 v[170:173], v115 offset:41536
	ds_read_b128 v[178:181], v115 offset:46144
	ds_read_b128 v[186:189], v100 offset:64
	ds_read_b128 v[194:197], v100 offset:4672
	s_setprio 1
	v_mfma_f32_32x32x16_bf16 v[82:97], v[190:193], v[166:169], v[82:97]
	v_mfma_f32_32x32x16_bf16 v[50:65], v[190:193], v[174:177], v[50:65]
	v_mfma_f32_32x32x16_bf16 v[2:17], v[190:193], v[182:185], v[2:17]
	s_waitcnt lgkmcnt(5)
	v_mfma_f32_32x32x16_bf16 v[66:81], v[198:201], v[166:169], v[66:81]
	v_mfma_f32_32x32x16_bf16 v[34:49], v[198:201], v[174:177], v[34:49]
	v_mfma_f32_32x32x16_bf16 v[18:33], v[198:201], v[182:185], v[18:33]
	s_setprio 0
	ds_read_b128 v[166:169], v115 offset:36960
	ds_read_b128 v[174:177], v115 offset:41568
	ds_read_b128 v[182:185], v115 offset:46176
	ds_read_b128 v[190:193], v100 offset:96
	ds_read_b128 v[198:201], v100 offset:4704
	s_setprio 1
	s_waitcnt lgkmcnt(6)
	v_mfma_f32_32x32x16_bf16 v[82:97], v[186:189], v[162:165], v[82:97]
	v_mfma_f32_32x32x16_bf16 v[50:65], v[186:189], v[170:173], v[50:65]
	v_mfma_f32_32x32x16_bf16 v[2:17], v[186:189], v[178:181], v[2:17]
	s_waitcnt lgkmcnt(5)
	v_mfma_f32_32x32x16_bf16 v[66:81], v[194:197], v[162:165], v[66:81]
	v_mfma_f32_32x32x16_bf16 v[34:49], v[194:197], v[170:173], v[34:49]
	v_mfma_f32_32x32x16_bf16 v[18:33], v[194:197], v[178:181], v[18:33]
	s_setprio 0
	s_setprio 1
	s_waitcnt lgkmcnt(1)
	v_mfma_f32_32x32x16_bf16 v[82:97], v[190:193], v[166:169], v[82:97]
	v_mfma_f32_32x32x16_bf16 v[50:65], v[190:193], v[174:177], v[50:65]
	v_mfma_f32_32x32x16_bf16 v[2:17], v[190:193], v[182:185], v[2:17]
	s_waitcnt lgkmcnt(0)
	v_mfma_f32_32x32x16_bf16 v[66:81], v[198:201], v[166:169], v[66:81]
	v_mfma_f32_32x32x16_bf16 v[34:49], v[198:201], v[174:177], v[34:49]
	v_mfma_f32_32x32x16_bf16 v[18:33], v[198:201], v[182:185], v[18:33]
	s_setprio 0
	s_barrier
	global_load_dwordx4 v[162:165], v[106:107], off offset:640
	global_load_dwordx4 v[166:169], v[108:109], off offset:640
	global_load_dwordx4 v[170:173], v[102:103], off offset:640
	global_load_dwordx4 v[174:177], v[104:105], off offset:640
	global_load_dwordx4 v[178:181], v[110:111], off offset:640
	global_load_dwordx4 v[182:185], v[112:113], off offset:640
	global_load_dwordx4 v[186:189], v[116:117], off offset:640
	s_waitcnt vmcnt(11)
	ds_write_b128 v114, v[140:143]
	ds_write_b128 v114, v[120:123] offset:9216
	ds_write_b128 v114, v[136:139] offset:18432
	s_waitcnt vmcnt(9)
	ds_write_b128 v114, v[148:151] offset:27648
	ds_write_b128 v114, v[144:147] offset:36864
	s_waitcnt vmcnt(8)
	ds_write_b128 v114, v[152:155] offset:46080
	s_waitcnt vmcnt(7)
	ds_write_b128 v114, v[156:159] offset:55296
	ds_read_b128 v[120:123], v98 offset:36864
	ds_read_b128 v[136:139], v98 offset:36896
	ds_read_b128 v[140:143], v98 offset:41472
	ds_read_b128 v[144:147], v98 offset:41504
	ds_read_b128 v[148:151], v98 offset:46080
	ds_read_b128 v[152:155], v98 offset:46112
	ds_read_b128 v[156:159], v101
	ds_read_b128 v[190:193], v101 offset:32
	ds_read_b128 v[194:197], v101 offset:4608
	ds_read_b128 v[198:201], v101 offset:4640
	s_setprio 1
	s_waitcnt lgkmcnt(3)
	v_mfma_f32_32x32x16_bf16 v[82:97], v[156:159], v[120:123], v[82:97]
	v_mfma_f32_32x32x16_bf16 v[50:65], v[156:159], v[140:143], v[50:65]
	v_mfma_f32_32x32x16_bf16 v[2:17], v[156:159], v[148:151], v[2:17]
	s_waitcnt lgkmcnt(1)
	v_mfma_f32_32x32x16_bf16 v[66:81], v[194:197], v[120:123], v[66:81]
	v_mfma_f32_32x32x16_bf16 v[34:49], v[194:197], v[140:143], v[34:49]
	v_mfma_f32_32x32x16_bf16 v[18:33], v[194:197], v[148:151], v[18:33]
	s_setprio 0
	ds_read_b128 v[120:123], v98 offset:36928
	ds_read_b128 v[140:143], v98 offset:41536
	ds_read_b128 v[148:151], v98 offset:46144
	ds_read_b128 v[156:159], v101 offset:64
	ds_read_b128 v[194:197], v101 offset:4672
	s_setprio 1
	v_mfma_f32_32x32x16_bf16 v[82:97], v[190:193], v[136:139], v[82:97]
	v_mfma_f32_32x32x16_bf16 v[50:65], v[190:193], v[144:147], v[50:65]
	v_mfma_f32_32x32x16_bf16 v[2:17], v[190:193], v[152:155], v[2:17]
	s_waitcnt lgkmcnt(5)
	v_mfma_f32_32x32x16_bf16 v[66:81], v[198:201], v[136:139], v[66:81]
	v_mfma_f32_32x32x16_bf16 v[34:49], v[198:201], v[144:147], v[34:49]
	v_mfma_f32_32x32x16_bf16 v[18:33], v[198:201], v[152:155], v[18:33]
	s_setprio 0
	ds_read_b128 v[136:139], v98 offset:36960
	ds_read_b128 v[144:147], v98 offset:41568
	ds_read_b128 v[152:155], v98 offset:46176
	ds_read_b128 v[190:193], v101 offset:96
	ds_read_b128 v[198:201], v101 offset:4704
	s_setprio 1
	s_waitcnt lgkmcnt(6)
	v_mfma_f32_32x32x16_bf16 v[82:97], v[156:159], v[120:123], v[82:97]
	v_mfma_f32_32x32x16_bf16 v[50:65], v[156:159], v[140:143], v[50:65]
	v_mfma_f32_32x32x16_bf16 v[2:17], v[156:159], v[148:151], v[2:17]
	s_waitcnt lgkmcnt(5)
	v_mfma_f32_32x32x16_bf16 v[66:81], v[194:197], v[120:123], v[66:81]
	v_mfma_f32_32x32x16_bf16 v[34:49], v[194:197], v[140:143], v[34:49]
	v_mfma_f32_32x32x16_bf16 v[18:33], v[194:197], v[148:151], v[18:33]
	s_setprio 0
	s_setprio 1
	s_waitcnt lgkmcnt(1)
	v_mfma_f32_32x32x16_bf16 v[82:97], v[190:193], v[136:139], v[82:97]
	v_mfma_f32_32x32x16_bf16 v[50:65], v[190:193], v[144:147], v[50:65]
	v_mfma_f32_32x32x16_bf16 v[2:17], v[190:193], v[152:155], v[2:17]
	s_waitcnt lgkmcnt(0)
	v_mfma_f32_32x32x16_bf16 v[66:81], v[198:201], v[136:139], v[66:81]
	v_mfma_f32_32x32x16_bf16 v[34:49], v[198:201], v[144:147], v[34:49]
	v_mfma_f32_32x32x16_bf16 v[18:33], v[198:201], v[152:155], v[18:33]
	s_setprio 0
	s_barrier
	global_load_dwordx4 v[120:123], v[106:107], off offset:768
	global_load_dwordx4 v[136:139], v[108:109], off offset:768
	global_load_dwordx4 v[140:143], v[102:103], off offset:768
	global_load_dwordx4 v[144:147], v[104:105], off offset:768
	global_load_dwordx4 v[148:151], v[110:111], off offset:768
	global_load_dwordx4 v[152:155], v[112:113], off offset:768
	global_load_dwordx4 v[156:159], v[116:117], off offset:768
	s_waitcnt vmcnt(11)
	ds_write_b128 v119, v[170:173]
	ds_write_b128 v119, v[162:165] offset:9216
	ds_write_b128 v119, v[166:169] offset:18432
	s_waitcnt vmcnt(9)
	ds_write_b128 v119, v[178:181] offset:27648
	ds_write_b128 v119, v[174:177] offset:36864
	s_waitcnt vmcnt(8)
	ds_write_b128 v119, v[182:185] offset:46080
	s_waitcnt vmcnt(7)
	ds_write_b128 v119, v[186:189] offset:55296
	ds_read_b128 v[162:165], v115 offset:36864
	ds_read_b128 v[166:169], v115 offset:36896
	ds_read_b128 v[170:173], v115 offset:41472
	ds_read_b128 v[174:177], v115 offset:41504
	ds_read_b128 v[178:181], v115 offset:46080
	ds_read_b128 v[182:185], v115 offset:46112
	ds_read_b128 v[186:189], v100
	ds_read_b128 v[190:193], v100 offset:32
	ds_read_b128 v[194:197], v100 offset:4608
	ds_read_b128 v[198:201], v100 offset:4640
	s_setprio 1
	s_waitcnt lgkmcnt(3)
	v_mfma_f32_32x32x16_bf16 v[82:97], v[186:189], v[162:165], v[82:97]
	v_mfma_f32_32x32x16_bf16 v[50:65], v[186:189], v[170:173], v[50:65]
	v_mfma_f32_32x32x16_bf16 v[2:17], v[186:189], v[178:181], v[2:17]
	s_waitcnt lgkmcnt(1)
	v_mfma_f32_32x32x16_bf16 v[66:81], v[194:197], v[162:165], v[66:81]
	v_mfma_f32_32x32x16_bf16 v[34:49], v[194:197], v[170:173], v[34:49]
	v_mfma_f32_32x32x16_bf16 v[18:33], v[194:197], v[178:181], v[18:33]
	s_setprio 0
	ds_read_b128 v[162:165], v115 offset:36928
	ds_read_b128 v[170:173], v115 offset:41536
	ds_read_b128 v[178:181], v115 offset:46144
	ds_read_b128 v[186:189], v100 offset:64
	ds_read_b128 v[194:197], v100 offset:4672
	s_setprio 1
	v_mfma_f32_32x32x16_bf16 v[82:97], v[190:193], v[166:169], v[82:97]
	v_mfma_f32_32x32x16_bf16 v[50:65], v[190:193], v[174:177], v[50:65]
	v_mfma_f32_32x32x16_bf16 v[2:17], v[190:193], v[182:185], v[2:17]
	s_waitcnt lgkmcnt(5)
	v_mfma_f32_32x32x16_bf16 v[66:81], v[198:201], v[166:169], v[66:81]
	v_mfma_f32_32x32x16_bf16 v[34:49], v[198:201], v[174:177], v[34:49]
	v_mfma_f32_32x32x16_bf16 v[18:33], v[198:201], v[182:185], v[18:33]
	s_setprio 0
	ds_read_b128 v[166:169], v115 offset:36960
	ds_read_b128 v[174:177], v115 offset:41568
	ds_read_b128 v[182:185], v115 offset:46176
	ds_read_b128 v[190:193], v100 offset:96
	ds_read_b128 v[198:201], v100 offset:4704
	s_setprio 1
	s_waitcnt lgkmcnt(6)
	v_mfma_f32_32x32x16_bf16 v[82:97], v[186:189], v[162:165], v[82:97]
	v_mfma_f32_32x32x16_bf16 v[50:65], v[186:189], v[170:173], v[50:65]
	v_mfma_f32_32x32x16_bf16 v[2:17], v[186:189], v[178:181], v[2:17]
	s_waitcnt lgkmcnt(5)
	v_mfma_f32_32x32x16_bf16 v[66:81], v[194:197], v[162:165], v[66:81]
	v_mfma_f32_32x32x16_bf16 v[34:49], v[194:197], v[170:173], v[34:49]
	v_mfma_f32_32x32x16_bf16 v[18:33], v[194:197], v[178:181], v[18:33]
	s_setprio 0
	s_setprio 1
	s_waitcnt lgkmcnt(1)
	v_mfma_f32_32x32x16_bf16 v[82:97], v[190:193], v[166:169], v[82:97]
	v_mfma_f32_32x32x16_bf16 v[50:65], v[190:193], v[174:177], v[50:65]
	v_mfma_f32_32x32x16_bf16 v[2:17], v[190:193], v[182:185], v[2:17]
	s_waitcnt lgkmcnt(0)
	v_mfma_f32_32x32x16_bf16 v[66:81], v[198:201], v[166:169], v[66:81]
	v_mfma_f32_32x32x16_bf16 v[34:49], v[198:201], v[174:177], v[34:49]
	v_mfma_f32_32x32x16_bf16 v[18:33], v[198:201], v[182:185], v[18:33]
	s_setprio 0
	s_barrier
	global_load_dwordx4 v[162:165], v[106:107], off offset:896
	global_load_dwordx4 v[166:169], v[108:109], off offset:896
	global_load_dwordx4 v[170:173], v[102:103], off offset:896
	global_load_dwordx4 v[174:177], v[104:105], off offset:896
	global_load_dwordx4 v[178:181], v[110:111], off offset:896
	global_load_dwordx4 v[182:185], v[112:113], off offset:896
	global_load_dwordx4 v[186:189], v[116:117], off offset:896
	s_waitcnt vmcnt(11)
	ds_write_b128 v114, v[140:143]
	ds_write_b128 v114, v[120:123] offset:9216
	ds_write_b128 v114, v[136:139] offset:18432
	s_waitcnt vmcnt(9)
	ds_write_b128 v114, v[148:151] offset:27648
	ds_write_b128 v114, v[144:147] offset:36864
	s_waitcnt vmcnt(8)
	ds_write_b128 v114, v[152:155] offset:46080
	s_waitcnt vmcnt(7)
	ds_write_b128 v114, v[156:159] offset:55296
	ds_read_b128 v[120:123], v98 offset:36864
	ds_read_b128 v[136:139], v98 offset:36896
	ds_read_b128 v[140:143], v98 offset:41472
	ds_read_b128 v[144:147], v98 offset:41504
	ds_read_b128 v[148:151], v98 offset:46080
	ds_read_b128 v[152:155], v98 offset:46112
	ds_read_b128 v[156:159], v101
	ds_read_b128 v[190:193], v101 offset:32
	ds_read_b128 v[194:197], v101 offset:4608
	ds_read_b128 v[198:201], v101 offset:4640
	s_setprio 1
	s_waitcnt lgkmcnt(3)
	v_mfma_f32_32x32x16_bf16 v[82:97], v[156:159], v[120:123], v[82:97]
	v_mfma_f32_32x32x16_bf16 v[50:65], v[156:159], v[140:143], v[50:65]
	v_mfma_f32_32x32x16_bf16 v[2:17], v[156:159], v[148:151], v[2:17]
	s_waitcnt lgkmcnt(1)
	v_mfma_f32_32x32x16_bf16 v[66:81], v[194:197], v[120:123], v[66:81]
	v_mfma_f32_32x32x16_bf16 v[34:49], v[194:197], v[140:143], v[34:49]
	v_mfma_f32_32x32x16_bf16 v[18:33], v[194:197], v[148:151], v[18:33]
	s_setprio 0
	ds_read_b128 v[120:123], v98 offset:36928
	ds_read_b128 v[140:143], v98 offset:41536
	ds_read_b128 v[148:151], v98 offset:46144
	ds_read_b128 v[156:159], v101 offset:64
	ds_read_b128 v[194:197], v101 offset:4672
	s_setprio 1
	v_mfma_f32_32x32x16_bf16 v[82:97], v[190:193], v[136:139], v[82:97]
	v_mfma_f32_32x32x16_bf16 v[50:65], v[190:193], v[144:147], v[50:65]
	v_mfma_f32_32x32x16_bf16 v[2:17], v[190:193], v[152:155], v[2:17]
	s_waitcnt lgkmcnt(5)
	v_mfma_f32_32x32x16_bf16 v[66:81], v[198:201], v[136:139], v[66:81]
	v_mfma_f32_32x32x16_bf16 v[34:49], v[198:201], v[144:147], v[34:49]
	v_mfma_f32_32x32x16_bf16 v[18:33], v[198:201], v[152:155], v[18:33]
	s_setprio 0
	ds_read_b128 v[136:139], v98 offset:36960
	ds_read_b128 v[144:147], v98 offset:41568
	ds_read_b128 v[152:155], v98 offset:46176
	ds_read_b128 v[190:193], v101 offset:96
	ds_read_b128 v[198:201], v101 offset:4704
	s_setprio 1
	s_waitcnt lgkmcnt(6)
	v_mfma_f32_32x32x16_bf16 v[82:97], v[156:159], v[120:123], v[82:97]
	v_mfma_f32_32x32x16_bf16 v[50:65], v[156:159], v[140:143], v[50:65]
	v_mfma_f32_32x32x16_bf16 v[2:17], v[156:159], v[148:151], v[2:17]
	s_waitcnt lgkmcnt(5)
	v_mfma_f32_32x32x16_bf16 v[66:81], v[194:197], v[120:123], v[66:81]
	v_mfma_f32_32x32x16_bf16 v[34:49], v[194:197], v[140:143], v[34:49]
	v_mfma_f32_32x32x16_bf16 v[18:33], v[194:197], v[148:151], v[18:33]
	s_setprio 0
	s_setprio 1
	s_waitcnt lgkmcnt(1)
	v_mfma_f32_32x32x16_bf16 v[82:97], v[190:193], v[136:139], v[82:97]
	v_mfma_f32_32x32x16_bf16 v[50:65], v[190:193], v[144:147], v[50:65]
	v_mfma_f32_32x32x16_bf16 v[2:17], v[190:193], v[152:155], v[2:17]
	s_waitcnt lgkmcnt(0)
	v_mfma_f32_32x32x16_bf16 v[66:81], v[198:201], v[136:139], v[66:81]
	v_mfma_f32_32x32x16_bf16 v[34:49], v[198:201], v[144:147], v[34:49]
	v_mfma_f32_32x32x16_bf16 v[18:33], v[198:201], v[152:155], v[18:33]
	s_setprio 0
	s_barrier
	global_load_dwordx4 v[120:123], v[106:107], off offset:1024
	global_load_dwordx4 v[136:139], v[108:109], off offset:1024
	global_load_dwordx4 v[140:143], v[102:103], off offset:1024
	global_load_dwordx4 v[144:147], v[104:105], off offset:1024
	global_load_dwordx4 v[148:151], v[110:111], off offset:1024
	global_load_dwordx4 v[152:155], v[112:113], off offset:1024
	global_load_dwordx4 v[156:159], v[116:117], off offset:1024
	s_waitcnt vmcnt(11)
	ds_write_b128 v119, v[170:173]
	ds_write_b128 v119, v[162:165] offset:9216
	ds_write_b128 v119, v[166:169] offset:18432
	s_waitcnt vmcnt(9)
	ds_write_b128 v119, v[178:181] offset:27648
	ds_write_b128 v119, v[174:177] offset:36864
	s_waitcnt vmcnt(8)
	ds_write_b128 v119, v[182:185] offset:46080
	s_waitcnt vmcnt(7)
	ds_write_b128 v119, v[186:189] offset:55296
	ds_read_b128 v[162:165], v115 offset:36864
	ds_read_b128 v[166:169], v115 offset:36896
	ds_read_b128 v[170:173], v115 offset:41472
	ds_read_b128 v[174:177], v115 offset:41504
	ds_read_b128 v[178:181], v115 offset:46080
	ds_read_b128 v[182:185], v115 offset:46112
	ds_read_b128 v[186:189], v100
	ds_read_b128 v[190:193], v100 offset:32
	ds_read_b128 v[194:197], v100 offset:4608
	ds_read_b128 v[198:201], v100 offset:4640
	s_setprio 1
	s_waitcnt lgkmcnt(3)
	v_mfma_f32_32x32x16_bf16 v[82:97], v[186:189], v[162:165], v[82:97]
	v_mfma_f32_32x32x16_bf16 v[50:65], v[186:189], v[170:173], v[50:65]
	v_mfma_f32_32x32x16_bf16 v[2:17], v[186:189], v[178:181], v[2:17]
	s_waitcnt lgkmcnt(1)
	v_mfma_f32_32x32x16_bf16 v[66:81], v[194:197], v[162:165], v[66:81]
	v_mfma_f32_32x32x16_bf16 v[34:49], v[194:197], v[170:173], v[34:49]
	v_mfma_f32_32x32x16_bf16 v[18:33], v[194:197], v[178:181], v[18:33]
	s_setprio 0
	ds_read_b128 v[162:165], v115 offset:36928
	ds_read_b128 v[170:173], v115 offset:41536
	ds_read_b128 v[178:181], v115 offset:46144
	ds_read_b128 v[186:189], v100 offset:64
	ds_read_b128 v[194:197], v100 offset:4672
	s_setprio 1
	v_mfma_f32_32x32x16_bf16 v[82:97], v[190:193], v[166:169], v[82:97]
	v_mfma_f32_32x32x16_bf16 v[50:65], v[190:193], v[174:177], v[50:65]
	v_mfma_f32_32x32x16_bf16 v[2:17], v[190:193], v[182:185], v[2:17]
	s_waitcnt lgkmcnt(5)
	v_mfma_f32_32x32x16_bf16 v[66:81], v[198:201], v[166:169], v[66:81]
	v_mfma_f32_32x32x16_bf16 v[34:49], v[198:201], v[174:177], v[34:49]
	v_mfma_f32_32x32x16_bf16 v[18:33], v[198:201], v[182:185], v[18:33]
	s_setprio 0
	ds_read_b128 v[166:169], v115 offset:36960
	ds_read_b128 v[174:177], v115 offset:41568
	ds_read_b128 v[182:185], v115 offset:46176
	ds_read_b128 v[190:193], v100 offset:96
	ds_read_b128 v[198:201], v100 offset:4704
	s_setprio 1
	s_waitcnt lgkmcnt(6)
	v_mfma_f32_32x32x16_bf16 v[82:97], v[186:189], v[162:165], v[82:97]
	v_mfma_f32_32x32x16_bf16 v[50:65], v[186:189], v[170:173], v[50:65]
	v_mfma_f32_32x32x16_bf16 v[2:17], v[186:189], v[178:181], v[2:17]
	s_waitcnt lgkmcnt(5)
	v_mfma_f32_32x32x16_bf16 v[66:81], v[194:197], v[162:165], v[66:81]
	v_mfma_f32_32x32x16_bf16 v[34:49], v[194:197], v[170:173], v[34:49]
	v_mfma_f32_32x32x16_bf16 v[18:33], v[194:197], v[178:181], v[18:33]
	s_setprio 0
	s_setprio 1
	s_waitcnt lgkmcnt(1)
	v_mfma_f32_32x32x16_bf16 v[82:97], v[190:193], v[166:169], v[82:97]
	v_mfma_f32_32x32x16_bf16 v[50:65], v[190:193], v[174:177], v[50:65]
	v_mfma_f32_32x32x16_bf16 v[2:17], v[190:193], v[182:185], v[2:17]
	s_waitcnt lgkmcnt(0)
	v_mfma_f32_32x32x16_bf16 v[66:81], v[198:201], v[166:169], v[66:81]
	v_mfma_f32_32x32x16_bf16 v[34:49], v[198:201], v[174:177], v[34:49]
	v_mfma_f32_32x32x16_bf16 v[18:33], v[198:201], v[182:185], v[18:33]
	s_setprio 0
	s_barrier
	global_load_dwordx4 v[162:165], v[106:107], off offset:1152
	global_load_dwordx4 v[166:169], v[108:109], off offset:1152
	global_load_dwordx4 v[170:173], v[102:103], off offset:1152
	global_load_dwordx4 v[174:177], v[104:105], off offset:1152
	global_load_dwordx4 v[178:181], v[110:111], off offset:1152
	global_load_dwordx4 v[182:185], v[112:113], off offset:1152
	global_load_dwordx4 v[186:189], v[116:117], off offset:1152
	s_waitcnt vmcnt(11)
	ds_write_b128 v114, v[140:143]
	ds_write_b128 v114, v[120:123] offset:9216
	ds_write_b128 v114, v[136:139] offset:18432
	s_waitcnt vmcnt(9)
	ds_write_b128 v114, v[148:151] offset:27648
	ds_write_b128 v114, v[144:147] offset:36864
	s_waitcnt vmcnt(8)
	ds_write_b128 v114, v[152:155] offset:46080
	s_waitcnt vmcnt(7)
	ds_write_b128 v114, v[156:159] offset:55296
	ds_read_b128 v[120:123], v98 offset:36864
	ds_read_b128 v[136:139], v98 offset:36896
	ds_read_b128 v[140:143], v98 offset:41472
	ds_read_b128 v[144:147], v98 offset:41504
	ds_read_b128 v[148:151], v98 offset:46080
	ds_read_b128 v[152:155], v98 offset:46112
	ds_read_b128 v[156:159], v101
	ds_read_b128 v[190:193], v101 offset:32
	ds_read_b128 v[194:197], v101 offset:4608
	ds_read_b128 v[198:201], v101 offset:4640
	s_setprio 1
	s_waitcnt lgkmcnt(3)
	v_mfma_f32_32x32x16_bf16 v[82:97], v[156:159], v[120:123], v[82:97]
	v_mfma_f32_32x32x16_bf16 v[50:65], v[156:159], v[140:143], v[50:65]
	v_mfma_f32_32x32x16_bf16 v[2:17], v[156:159], v[148:151], v[2:17]
	s_waitcnt lgkmcnt(1)
	v_mfma_f32_32x32x16_bf16 v[66:81], v[194:197], v[120:123], v[66:81]
	v_mfma_f32_32x32x16_bf16 v[34:49], v[194:197], v[140:143], v[34:49]
	v_mfma_f32_32x32x16_bf16 v[18:33], v[194:197], v[148:151], v[18:33]
	s_setprio 0
	ds_read_b128 v[120:123], v98 offset:36928
	ds_read_b128 v[140:143], v98 offset:41536
	ds_read_b128 v[148:151], v98 offset:46144
	ds_read_b128 v[156:159], v101 offset:64
	ds_read_b128 v[194:197], v101 offset:4672
	s_setprio 1
	v_mfma_f32_32x32x16_bf16 v[82:97], v[190:193], v[136:139], v[82:97]
	v_mfma_f32_32x32x16_bf16 v[50:65], v[190:193], v[144:147], v[50:65]
	v_mfma_f32_32x32x16_bf16 v[2:17], v[190:193], v[152:155], v[2:17]
	s_waitcnt lgkmcnt(5)
	v_mfma_f32_32x32x16_bf16 v[66:81], v[198:201], v[136:139], v[66:81]
	v_mfma_f32_32x32x16_bf16 v[34:49], v[198:201], v[144:147], v[34:49]
	v_mfma_f32_32x32x16_bf16 v[18:33], v[198:201], v[152:155], v[18:33]
	s_setprio 0
	ds_read_b128 v[136:139], v98 offset:36960
	ds_read_b128 v[144:147], v98 offset:41568
	ds_read_b128 v[152:155], v98 offset:46176
	ds_read_b128 v[190:193], v101 offset:96
	ds_read_b128 v[198:201], v101 offset:4704
	s_setprio 1
	s_waitcnt lgkmcnt(6)
	v_mfma_f32_32x32x16_bf16 v[82:97], v[156:159], v[120:123], v[82:97]
	v_mfma_f32_32x32x16_bf16 v[50:65], v[156:159], v[140:143], v[50:65]
	v_mfma_f32_32x32x16_bf16 v[2:17], v[156:159], v[148:151], v[2:17]
	s_waitcnt lgkmcnt(5)
	v_mfma_f32_32x32x16_bf16 v[66:81], v[194:197], v[120:123], v[66:81]
	v_mfma_f32_32x32x16_bf16 v[34:49], v[194:197], v[140:143], v[34:49]
	v_mfma_f32_32x32x16_bf16 v[18:33], v[194:197], v[148:151], v[18:33]
	s_setprio 0
	s_setprio 1
	s_waitcnt lgkmcnt(1)
	v_mfma_f32_32x32x16_bf16 v[82:97], v[190:193], v[136:139], v[82:97]
	v_mfma_f32_32x32x16_bf16 v[50:65], v[190:193], v[144:147], v[50:65]
	v_mfma_f32_32x32x16_bf16 v[2:17], v[190:193], v[152:155], v[2:17]
	s_waitcnt lgkmcnt(0)
	v_mfma_f32_32x32x16_bf16 v[66:81], v[198:201], v[136:139], v[66:81]
	v_mfma_f32_32x32x16_bf16 v[34:49], v[198:201], v[144:147], v[34:49]
	v_mfma_f32_32x32x16_bf16 v[18:33], v[198:201], v[152:155], v[18:33]
	s_setprio 0
	s_barrier
	global_load_dwordx4 v[120:123], v[106:107], off offset:1280
	global_load_dwordx4 v[136:139], v[108:109], off offset:1280
	global_load_dwordx4 v[140:143], v[102:103], off offset:1280
	global_load_dwordx4 v[144:147], v[104:105], off offset:1280
	global_load_dwordx4 v[148:151], v[110:111], off offset:1280
	global_load_dwordx4 v[152:155], v[112:113], off offset:1280
	global_load_dwordx4 v[156:159], v[116:117], off offset:1280
	s_waitcnt vmcnt(11)
	ds_write_b128 v119, v[170:173]
	ds_write_b128 v119, v[162:165] offset:9216
	ds_write_b128 v119, v[166:169] offset:18432
	s_waitcnt vmcnt(9)
	ds_write_b128 v119, v[178:181] offset:27648
	ds_write_b128 v119, v[174:177] offset:36864
	s_waitcnt vmcnt(8)
	ds_write_b128 v119, v[182:185] offset:46080
	s_waitcnt vmcnt(7)
	ds_write_b128 v119, v[186:189] offset:55296
	ds_read_b128 v[162:165], v115 offset:36864
	ds_read_b128 v[166:169], v115 offset:36896
	ds_read_b128 v[170:173], v115 offset:41472
	ds_read_b128 v[174:177], v115 offset:41504
	ds_read_b128 v[178:181], v115 offset:46080
	ds_read_b128 v[182:185], v115 offset:46112
	ds_read_b128 v[186:189], v100
	ds_read_b128 v[190:193], v100 offset:32
	ds_read_b128 v[194:197], v100 offset:4608
	ds_read_b128 v[198:201], v100 offset:4640
	s_setprio 1
	s_waitcnt lgkmcnt(3)
	v_mfma_f32_32x32x16_bf16 v[82:97], v[186:189], v[162:165], v[82:97]
	v_mfma_f32_32x32x16_bf16 v[50:65], v[186:189], v[170:173], v[50:65]
	v_mfma_f32_32x32x16_bf16 v[2:17], v[186:189], v[178:181], v[2:17]
	s_waitcnt lgkmcnt(1)
	v_mfma_f32_32x32x16_bf16 v[66:81], v[194:197], v[162:165], v[66:81]
	v_mfma_f32_32x32x16_bf16 v[34:49], v[194:197], v[170:173], v[34:49]
	v_mfma_f32_32x32x16_bf16 v[18:33], v[194:197], v[178:181], v[18:33]
	s_setprio 0
	ds_read_b128 v[162:165], v115 offset:36928
	ds_read_b128 v[170:173], v115 offset:41536
	ds_read_b128 v[178:181], v115 offset:46144
	ds_read_b128 v[186:189], v100 offset:64
	ds_read_b128 v[194:197], v100 offset:4672
	s_setprio 1
	v_mfma_f32_32x32x16_bf16 v[82:97], v[190:193], v[166:169], v[82:97]
	v_mfma_f32_32x32x16_bf16 v[50:65], v[190:193], v[174:177], v[50:65]
	v_mfma_f32_32x32x16_bf16 v[2:17], v[190:193], v[182:185], v[2:17]
	s_waitcnt lgkmcnt(5)
	v_mfma_f32_32x32x16_bf16 v[66:81], v[198:201], v[166:169], v[66:81]
	v_mfma_f32_32x32x16_bf16 v[34:49], v[198:201], v[174:177], v[34:49]
	v_mfma_f32_32x32x16_bf16 v[18:33], v[198:201], v[182:185], v[18:33]
	s_setprio 0
	ds_read_b128 v[166:169], v115 offset:36960
	ds_read_b128 v[174:177], v115 offset:41568
	ds_read_b128 v[182:185], v115 offset:46176
	ds_read_b128 v[190:193], v100 offset:96
	ds_read_b128 v[198:201], v100 offset:4704
	s_setprio 1
	s_waitcnt lgkmcnt(6)
	v_mfma_f32_32x32x16_bf16 v[82:97], v[186:189], v[162:165], v[82:97]
	v_mfma_f32_32x32x16_bf16 v[50:65], v[186:189], v[170:173], v[50:65]
	v_mfma_f32_32x32x16_bf16 v[2:17], v[186:189], v[178:181], v[2:17]
	s_waitcnt lgkmcnt(5)
	v_mfma_f32_32x32x16_bf16 v[66:81], v[194:197], v[162:165], v[66:81]
	v_mfma_f32_32x32x16_bf16 v[34:49], v[194:197], v[170:173], v[34:49]
	v_mfma_f32_32x32x16_bf16 v[18:33], v[194:197], v[178:181], v[18:33]
	s_setprio 0
	s_setprio 1
	s_waitcnt lgkmcnt(1)
	v_mfma_f32_32x32x16_bf16 v[82:97], v[190:193], v[166:169], v[82:97]
	v_mfma_f32_32x32x16_bf16 v[50:65], v[190:193], v[174:177], v[50:65]
	v_mfma_f32_32x32x16_bf16 v[2:17], v[190:193], v[182:185], v[2:17]
	s_waitcnt lgkmcnt(0)
	v_mfma_f32_32x32x16_bf16 v[66:81], v[198:201], v[166:169], v[66:81]
	v_mfma_f32_32x32x16_bf16 v[34:49], v[198:201], v[174:177], v[34:49]
	v_mfma_f32_32x32x16_bf16 v[18:33], v[198:201], v[182:185], v[18:33]
	s_setprio 0
	s_barrier
	global_load_dwordx4 v[162:165], v[106:107], off offset:1408
	global_load_dwordx4 v[166:169], v[108:109], off offset:1408
	global_load_dwordx4 v[170:173], v[102:103], off offset:1408
	global_load_dwordx4 v[174:177], v[104:105], off offset:1408
	global_load_dwordx4 v[178:181], v[110:111], off offset:1408
	global_load_dwordx4 v[182:185], v[112:113], off offset:1408
	global_load_dwordx4 v[186:189], v[116:117], off offset:1408
	s_waitcnt vmcnt(11)
	ds_write_b128 v114, v[140:143]
	ds_write_b128 v114, v[120:123] offset:9216
	ds_write_b128 v114, v[136:139] offset:18432
	s_waitcnt vmcnt(9)
	ds_write_b128 v114, v[148:151] offset:27648
	ds_write_b128 v114, v[144:147] offset:36864
	s_waitcnt vmcnt(8)
	ds_write_b128 v114, v[152:155] offset:46080
	s_waitcnt vmcnt(7)
	ds_write_b128 v114, v[156:159] offset:55296
	ds_read_b128 v[120:123], v98 offset:36864
	ds_read_b128 v[136:139], v98 offset:36896
	ds_read_b128 v[140:143], v98 offset:41472
	ds_read_b128 v[144:147], v98 offset:41504
	ds_read_b128 v[148:151], v98 offset:46080
	ds_read_b128 v[152:155], v98 offset:46112
	ds_read_b128 v[156:159], v101
	ds_read_b128 v[190:193], v101 offset:32
	ds_read_b128 v[194:197], v101 offset:4608
	ds_read_b128 v[198:201], v101 offset:4640
	s_setprio 1
	s_waitcnt lgkmcnt(3)
	v_mfma_f32_32x32x16_bf16 v[82:97], v[156:159], v[120:123], v[82:97]
	v_mfma_f32_32x32x16_bf16 v[50:65], v[156:159], v[140:143], v[50:65]
	v_mfma_f32_32x32x16_bf16 v[2:17], v[156:159], v[148:151], v[2:17]
	s_waitcnt lgkmcnt(1)
	v_mfma_f32_32x32x16_bf16 v[66:81], v[194:197], v[120:123], v[66:81]
	v_mfma_f32_32x32x16_bf16 v[34:49], v[194:197], v[140:143], v[34:49]
	v_mfma_f32_32x32x16_bf16 v[18:33], v[194:197], v[148:151], v[18:33]
	s_setprio 0
	ds_read_b128 v[120:123], v98 offset:36928
	ds_read_b128 v[140:143], v98 offset:41536
	ds_read_b128 v[148:151], v98 offset:46144
	ds_read_b128 v[156:159], v101 offset:64
	ds_read_b128 v[194:197], v101 offset:4672
	s_setprio 1
	v_mfma_f32_32x32x16_bf16 v[82:97], v[190:193], v[136:139], v[82:97]
	v_mfma_f32_32x32x16_bf16 v[50:65], v[190:193], v[144:147], v[50:65]
	v_mfma_f32_32x32x16_bf16 v[2:17], v[190:193], v[152:155], v[2:17]
	s_waitcnt lgkmcnt(5)
	v_mfma_f32_32x32x16_bf16 v[66:81], v[198:201], v[136:139], v[66:81]
	v_mfma_f32_32x32x16_bf16 v[34:49], v[198:201], v[144:147], v[34:49]
	v_mfma_f32_32x32x16_bf16 v[18:33], v[198:201], v[152:155], v[18:33]
	s_setprio 0
	ds_read_b128 v[136:139], v98 offset:36960
	ds_read_b128 v[144:147], v98 offset:41568
	ds_read_b128 v[152:155], v98 offset:46176
	ds_read_b128 v[190:193], v101 offset:96
	ds_read_b128 v[198:201], v101 offset:4704
	s_setprio 1
	s_waitcnt lgkmcnt(6)
	v_mfma_f32_32x32x16_bf16 v[82:97], v[156:159], v[120:123], v[82:97]
	v_mfma_f32_32x32x16_bf16 v[50:65], v[156:159], v[140:143], v[50:65]
	v_mfma_f32_32x32x16_bf16 v[2:17], v[156:159], v[148:151], v[2:17]
	s_waitcnt lgkmcnt(5)
	v_mfma_f32_32x32x16_bf16 v[66:81], v[194:197], v[120:123], v[66:81]
	v_mfma_f32_32x32x16_bf16 v[34:49], v[194:197], v[140:143], v[34:49]
	v_mfma_f32_32x32x16_bf16 v[18:33], v[194:197], v[148:151], v[18:33]
	s_setprio 0
	s_setprio 1
	s_waitcnt lgkmcnt(1)
	v_mfma_f32_32x32x16_bf16 v[82:97], v[190:193], v[136:139], v[82:97]
	v_mfma_f32_32x32x16_bf16 v[50:65], v[190:193], v[144:147], v[50:65]
	v_mfma_f32_32x32x16_bf16 v[2:17], v[190:193], v[152:155], v[2:17]
	s_waitcnt lgkmcnt(0)
	v_mfma_f32_32x32x16_bf16 v[66:81], v[198:201], v[136:139], v[66:81]
	v_mfma_f32_32x32x16_bf16 v[34:49], v[198:201], v[144:147], v[34:49]
	v_mfma_f32_32x32x16_bf16 v[18:33], v[198:201], v[152:155], v[18:33]
	s_setprio 0
	s_barrier
	global_load_dwordx4 v[120:123], v[106:107], off offset:1536
	global_load_dwordx4 v[136:139], v[108:109], off offset:1536
	global_load_dwordx4 v[140:143], v[102:103], off offset:1536
	global_load_dwordx4 v[144:147], v[104:105], off offset:1536
	global_load_dwordx4 v[148:151], v[110:111], off offset:1536
	global_load_dwordx4 v[152:155], v[112:113], off offset:1536
	global_load_dwordx4 v[156:159], v[116:117], off offset:1536
	s_waitcnt vmcnt(11)
	ds_write_b128 v119, v[170:173]
	ds_write_b128 v119, v[162:165] offset:9216
	ds_write_b128 v119, v[166:169] offset:18432
	s_waitcnt vmcnt(9)
	ds_write_b128 v119, v[178:181] offset:27648
	ds_write_b128 v119, v[174:177] offset:36864
	s_waitcnt vmcnt(8)
	ds_write_b128 v119, v[182:185] offset:46080
	s_waitcnt vmcnt(7)
	ds_write_b128 v119, v[186:189] offset:55296
	ds_read_b128 v[162:165], v115 offset:36864
	ds_read_b128 v[166:169], v115 offset:36896
	ds_read_b128 v[170:173], v115 offset:41472
	ds_read_b128 v[174:177], v115 offset:41504
	ds_read_b128 v[178:181], v115 offset:46080
	ds_read_b128 v[182:185], v115 offset:46112
	ds_read_b128 v[186:189], v100
	ds_read_b128 v[190:193], v100 offset:32
	ds_read_b128 v[194:197], v100 offset:4608
	ds_read_b128 v[198:201], v100 offset:4640
	s_setprio 1
	s_waitcnt lgkmcnt(3)
	v_mfma_f32_32x32x16_bf16 v[82:97], v[186:189], v[162:165], v[82:97]
	v_mfma_f32_32x32x16_bf16 v[50:65], v[186:189], v[170:173], v[50:65]
	v_mfma_f32_32x32x16_bf16 v[2:17], v[186:189], v[178:181], v[2:17]
	s_waitcnt lgkmcnt(1)
	v_mfma_f32_32x32x16_bf16 v[66:81], v[194:197], v[162:165], v[66:81]
	v_mfma_f32_32x32x16_bf16 v[34:49], v[194:197], v[170:173], v[34:49]
	v_mfma_f32_32x32x16_bf16 v[18:33], v[194:197], v[178:181], v[18:33]
	s_setprio 0
	ds_read_b128 v[162:165], v115 offset:36928
	ds_read_b128 v[170:173], v115 offset:41536
	ds_read_b128 v[178:181], v115 offset:46144
	ds_read_b128 v[186:189], v100 offset:64
	ds_read_b128 v[194:197], v100 offset:4672
	s_setprio 1
	v_mfma_f32_32x32x16_bf16 v[82:97], v[190:193], v[166:169], v[82:97]
	v_mfma_f32_32x32x16_bf16 v[50:65], v[190:193], v[174:177], v[50:65]
	v_mfma_f32_32x32x16_bf16 v[2:17], v[190:193], v[182:185], v[2:17]
	s_waitcnt lgkmcnt(5)
	v_mfma_f32_32x32x16_bf16 v[66:81], v[198:201], v[166:169], v[66:81]
	v_mfma_f32_32x32x16_bf16 v[34:49], v[198:201], v[174:177], v[34:49]
	v_mfma_f32_32x32x16_bf16 v[18:33], v[198:201], v[182:185], v[18:33]
	s_setprio 0
	ds_read_b128 v[166:169], v115 offset:36960
	ds_read_b128 v[174:177], v115 offset:41568
	ds_read_b128 v[182:185], v115 offset:46176
	ds_read_b128 v[190:193], v100 offset:96
	ds_read_b128 v[198:201], v100 offset:4704
	s_setprio 1
	s_waitcnt lgkmcnt(6)
	v_mfma_f32_32x32x16_bf16 v[82:97], v[186:189], v[162:165], v[82:97]
	v_mfma_f32_32x32x16_bf16 v[50:65], v[186:189], v[170:173], v[50:65]
	v_mfma_f32_32x32x16_bf16 v[2:17], v[186:189], v[178:181], v[2:17]
	s_waitcnt lgkmcnt(5)
	v_mfma_f32_32x32x16_bf16 v[66:81], v[194:197], v[162:165], v[66:81]
	v_mfma_f32_32x32x16_bf16 v[34:49], v[194:197], v[170:173], v[34:49]
	v_mfma_f32_32x32x16_bf16 v[18:33], v[194:197], v[178:181], v[18:33]
	s_setprio 0
	s_setprio 1
	s_waitcnt lgkmcnt(1)
	v_mfma_f32_32x32x16_bf16 v[82:97], v[190:193], v[166:169], v[82:97]
	v_mfma_f32_32x32x16_bf16 v[50:65], v[190:193], v[174:177], v[50:65]
	v_mfma_f32_32x32x16_bf16 v[2:17], v[190:193], v[182:185], v[2:17]
	s_waitcnt lgkmcnt(0)
	v_mfma_f32_32x32x16_bf16 v[66:81], v[198:201], v[166:169], v[66:81]
	v_mfma_f32_32x32x16_bf16 v[34:49], v[198:201], v[174:177], v[34:49]
	v_mfma_f32_32x32x16_bf16 v[18:33], v[198:201], v[182:185], v[18:33]
	s_setprio 0
	s_barrier
	global_load_dwordx4 v[162:165], v[106:107], off offset:1664
	global_load_dwordx4 v[166:169], v[108:109], off offset:1664
	global_load_dwordx4 v[170:173], v[102:103], off offset:1664
	global_load_dwordx4 v[174:177], v[104:105], off offset:1664
	global_load_dwordx4 v[178:181], v[110:111], off offset:1664
	global_load_dwordx4 v[182:185], v[112:113], off offset:1664
	global_load_dwordx4 v[186:189], v[116:117], off offset:1664
	s_waitcnt vmcnt(11)
	ds_write_b128 v114, v[140:143]
	ds_write_b128 v114, v[120:123] offset:9216
	ds_write_b128 v114, v[136:139] offset:18432
	s_waitcnt vmcnt(9)
	ds_write_b128 v114, v[148:151] offset:27648
	ds_write_b128 v114, v[144:147] offset:36864
	s_waitcnt vmcnt(8)
	ds_write_b128 v114, v[152:155] offset:46080
	s_waitcnt vmcnt(7)
	ds_write_b128 v114, v[156:159] offset:55296
	ds_read_b128 v[120:123], v98 offset:36864
	ds_read_b128 v[136:139], v98 offset:36896
	ds_read_b128 v[140:143], v98 offset:41472
	ds_read_b128 v[144:147], v98 offset:41504
	ds_read_b128 v[148:151], v98 offset:46080
	ds_read_b128 v[152:155], v98 offset:46112
	ds_read_b128 v[156:159], v101
	ds_read_b128 v[190:193], v101 offset:32
	ds_read_b128 v[194:197], v101 offset:4608
	ds_read_b128 v[198:201], v101 offset:4640
	s_setprio 1
	s_waitcnt lgkmcnt(3)
	v_mfma_f32_32x32x16_bf16 v[82:97], v[156:159], v[120:123], v[82:97]
	v_mfma_f32_32x32x16_bf16 v[50:65], v[156:159], v[140:143], v[50:65]
	v_mfma_f32_32x32x16_bf16 v[2:17], v[156:159], v[148:151], v[2:17]
	s_waitcnt lgkmcnt(1)
	v_mfma_f32_32x32x16_bf16 v[66:81], v[194:197], v[120:123], v[66:81]
	v_mfma_f32_32x32x16_bf16 v[34:49], v[194:197], v[140:143], v[34:49]
	v_mfma_f32_32x32x16_bf16 v[18:33], v[194:197], v[148:151], v[18:33]
	s_setprio 0
	ds_read_b128 v[120:123], v98 offset:36928
	ds_read_b128 v[140:143], v98 offset:41536
	ds_read_b128 v[148:151], v98 offset:46144
	ds_read_b128 v[156:159], v101 offset:64
	ds_read_b128 v[194:197], v101 offset:4672
	s_setprio 1
	v_mfma_f32_32x32x16_bf16 v[82:97], v[190:193], v[136:139], v[82:97]
	v_mfma_f32_32x32x16_bf16 v[50:65], v[190:193], v[144:147], v[50:65]
	v_mfma_f32_32x32x16_bf16 v[2:17], v[190:193], v[152:155], v[2:17]
	s_waitcnt lgkmcnt(5)
	v_mfma_f32_32x32x16_bf16 v[66:81], v[198:201], v[136:139], v[66:81]
	v_mfma_f32_32x32x16_bf16 v[34:49], v[198:201], v[144:147], v[34:49]
	v_mfma_f32_32x32x16_bf16 v[18:33], v[198:201], v[152:155], v[18:33]
	s_setprio 0
	ds_read_b128 v[136:139], v98 offset:36960
	ds_read_b128 v[144:147], v98 offset:41568
	ds_read_b128 v[152:155], v98 offset:46176
	ds_read_b128 v[190:193], v101 offset:96
	ds_read_b128 v[198:201], v101 offset:4704
	s_setprio 1
	s_waitcnt lgkmcnt(6)
	v_mfma_f32_32x32x16_bf16 v[82:97], v[156:159], v[120:123], v[82:97]
	v_mfma_f32_32x32x16_bf16 v[50:65], v[156:159], v[140:143], v[50:65]
	v_mfma_f32_32x32x16_bf16 v[2:17], v[156:159], v[148:151], v[2:17]
	s_waitcnt lgkmcnt(5)
	v_mfma_f32_32x32x16_bf16 v[66:81], v[194:197], v[120:123], v[66:81]
	v_mfma_f32_32x32x16_bf16 v[34:49], v[194:197], v[140:143], v[34:49]
	v_mfma_f32_32x32x16_bf16 v[18:33], v[194:197], v[148:151], v[18:33]
	s_setprio 0
	s_setprio 1
	s_waitcnt lgkmcnt(1)
	v_mfma_f32_32x32x16_bf16 v[82:97], v[190:193], v[136:139], v[82:97]
	v_mfma_f32_32x32x16_bf16 v[50:65], v[190:193], v[144:147], v[50:65]
	v_mfma_f32_32x32x16_bf16 v[2:17], v[190:193], v[152:155], v[2:17]
	s_waitcnt lgkmcnt(0)
	v_mfma_f32_32x32x16_bf16 v[66:81], v[198:201], v[136:139], v[66:81]
	v_mfma_f32_32x32x16_bf16 v[34:49], v[198:201], v[144:147], v[34:49]
	v_mfma_f32_32x32x16_bf16 v[18:33], v[198:201], v[152:155], v[18:33]
	s_setprio 0
	s_barrier
	global_load_dwordx4 v[120:123], v[106:107], off offset:1792
	global_load_dwordx4 v[136:139], v[108:109], off offset:1792
	global_load_dwordx4 v[140:143], v[102:103], off offset:1792
	global_load_dwordx4 v[144:147], v[104:105], off offset:1792
	global_load_dwordx4 v[148:151], v[110:111], off offset:1792
	global_load_dwordx4 v[152:155], v[112:113], off offset:1792
	global_load_dwordx4 v[156:159], v[116:117], off offset:1792
	s_waitcnt vmcnt(11)
	ds_write_b128 v119, v[170:173]
	ds_write_b128 v119, v[162:165] offset:9216
	ds_write_b128 v119, v[166:169] offset:18432
	s_waitcnt vmcnt(9)
	ds_write_b128 v119, v[178:181] offset:27648
	ds_write_b128 v119, v[174:177] offset:36864
	s_waitcnt vmcnt(8)
	ds_write_b128 v119, v[182:185] offset:46080
	s_waitcnt vmcnt(7)
	ds_write_b128 v119, v[186:189] offset:55296
	ds_read_b128 v[162:165], v115 offset:36864
	ds_read_b128 v[166:169], v115 offset:36896
	ds_read_b128 v[170:173], v115 offset:41472
	ds_read_b128 v[174:177], v115 offset:41504
	ds_read_b128 v[178:181], v115 offset:46080
	ds_read_b128 v[182:185], v115 offset:46112
	ds_read_b128 v[186:189], v100
	ds_read_b128 v[190:193], v100 offset:32
	ds_read_b128 v[194:197], v100 offset:4608
	ds_read_b128 v[198:201], v100 offset:4640
	s_setprio 1
	s_waitcnt lgkmcnt(3)
	v_mfma_f32_32x32x16_bf16 v[82:97], v[186:189], v[162:165], v[82:97]
	v_mfma_f32_32x32x16_bf16 v[50:65], v[186:189], v[170:173], v[50:65]
	v_mfma_f32_32x32x16_bf16 v[2:17], v[186:189], v[178:181], v[2:17]
	s_waitcnt lgkmcnt(1)
	v_mfma_f32_32x32x16_bf16 v[66:81], v[194:197], v[162:165], v[66:81]
	v_mfma_f32_32x32x16_bf16 v[34:49], v[194:197], v[170:173], v[34:49]
	v_mfma_f32_32x32x16_bf16 v[18:33], v[194:197], v[178:181], v[18:33]
	s_setprio 0
	ds_read_b128 v[162:165], v115 offset:36928
	ds_read_b128 v[170:173], v115 offset:41536
	ds_read_b128 v[178:181], v115 offset:46144
	ds_read_b128 v[186:189], v100 offset:64
	ds_read_b128 v[194:197], v100 offset:4672
	s_setprio 1
	v_mfma_f32_32x32x16_bf16 v[82:97], v[190:193], v[166:169], v[82:97]
	v_mfma_f32_32x32x16_bf16 v[50:65], v[190:193], v[174:177], v[50:65]
	v_mfma_f32_32x32x16_bf16 v[2:17], v[190:193], v[182:185], v[2:17]
	s_waitcnt lgkmcnt(5)
	v_mfma_f32_32x32x16_bf16 v[66:81], v[198:201], v[166:169], v[66:81]
	v_mfma_f32_32x32x16_bf16 v[34:49], v[198:201], v[174:177], v[34:49]
	v_mfma_f32_32x32x16_bf16 v[18:33], v[198:201], v[182:185], v[18:33]
	s_setprio 0
	ds_read_b128 v[166:169], v115 offset:36960
	ds_read_b128 v[174:177], v115 offset:41568
	ds_read_b128 v[182:185], v115 offset:46176
	ds_read_b128 v[190:193], v100 offset:96
	ds_read_b128 v[198:201], v100 offset:4704
	s_setprio 1
	s_waitcnt lgkmcnt(6)
	v_mfma_f32_32x32x16_bf16 v[82:97], v[186:189], v[162:165], v[82:97]
	v_mfma_f32_32x32x16_bf16 v[50:65], v[186:189], v[170:173], v[50:65]
	v_mfma_f32_32x32x16_bf16 v[2:17], v[186:189], v[178:181], v[2:17]
	s_waitcnt lgkmcnt(5)
	v_mfma_f32_32x32x16_bf16 v[66:81], v[194:197], v[162:165], v[66:81]
	v_mfma_f32_32x32x16_bf16 v[34:49], v[194:197], v[170:173], v[34:49]
	v_mfma_f32_32x32x16_bf16 v[18:33], v[194:197], v[178:181], v[18:33]
	s_setprio 0
	s_setprio 1
	s_waitcnt lgkmcnt(1)
	v_mfma_f32_32x32x16_bf16 v[82:97], v[190:193], v[166:169], v[82:97]
	v_mfma_f32_32x32x16_bf16 v[50:65], v[190:193], v[174:177], v[50:65]
	v_mfma_f32_32x32x16_bf16 v[2:17], v[190:193], v[182:185], v[2:17]
	s_waitcnt lgkmcnt(0)
	v_mfma_f32_32x32x16_bf16 v[66:81], v[198:201], v[166:169], v[66:81]
	v_mfma_f32_32x32x16_bf16 v[34:49], v[198:201], v[174:177], v[34:49]
	v_mfma_f32_32x32x16_bf16 v[18:33], v[198:201], v[182:185], v[18:33]
	s_setprio 0
	s_barrier
	global_load_dwordx4 v[162:165], v[106:107], off offset:1920
	s_nop 0
	global_load_dwordx4 v[106:109], v[108:109], off offset:1920
	s_nop 0
	global_load_dwordx4 v[166:169], v[102:103], off offset:1920
	s_nop 0
	global_load_dwordx4 v[102:105], v[104:105], off offset:1920
	s_nop 0
	global_load_dwordx4 v[170:173], v[110:111], off offset:1920
	s_nop 0
	global_load_dwordx4 v[110:113], v[112:113], off offset:1920
	s_nop 0
	global_load_dwordx4 v[174:177], v[116:117], off offset:1920
	s_waitcnt vmcnt(11)
	ds_write_b128 v114, v[140:143]
	ds_write_b128 v114, v[120:123] offset:9216
	ds_write_b128 v114, v[136:139] offset:18432
	s_waitcnt vmcnt(9)
	ds_write_b128 v114, v[148:151] offset:27648
	ds_write_b128 v114, v[144:147] offset:36864
	s_waitcnt vmcnt(8)
	ds_write_b128 v114, v[152:155] offset:46080
	s_waitcnt vmcnt(7)
	ds_write_b128 v114, v[156:159] offset:55296
	ds_read_b128 v[120:123], v98 offset:36864
	ds_read_b128 v[136:139], v98 offset:36896
	ds_read_b128 v[140:143], v98 offset:41472
	ds_read_b128 v[144:147], v98 offset:41504
	ds_read_b128 v[148:151], v98 offset:46080
	ds_read_b128 v[152:155], v98 offset:46112
	ds_read_b128 v[156:159], v101
	ds_read_b128 v[178:181], v101 offset:32
	ds_read_b128 v[182:185], v101 offset:4608
	ds_read_b128 v[186:189], v101 offset:4640
	s_setprio 1
	s_waitcnt lgkmcnt(3)
	v_mfma_f32_32x32x16_bf16 v[82:97], v[156:159], v[120:123], v[82:97]
	v_mfma_f32_32x32x16_bf16 v[50:65], v[156:159], v[140:143], v[50:65]
	v_mfma_f32_32x32x16_bf16 v[2:17], v[156:159], v[148:151], v[2:17]
	s_waitcnt lgkmcnt(1)
	v_mfma_f32_32x32x16_bf16 v[66:81], v[182:185], v[120:123], v[66:81]
	v_mfma_f32_32x32x16_bf16 v[34:49], v[182:185], v[140:143], v[34:49]
	v_mfma_f32_32x32x16_bf16 v[18:33], v[182:185], v[148:151], v[18:33]
	s_setprio 0
	ds_read_b128 v[120:123], v98 offset:36928
	ds_read_b128 v[140:143], v98 offset:41536
	ds_read_b128 v[148:151], v98 offset:46144
	ds_read_b128 v[156:159], v101 offset:64
	ds_read_b128 v[182:185], v101 offset:4672
	s_setprio 1
	v_mfma_f32_32x32x16_bf16 v[82:97], v[178:181], v[136:139], v[82:97]
	v_mfma_f32_32x32x16_bf16 v[50:65], v[178:181], v[144:147], v[50:65]
	v_mfma_f32_32x32x16_bf16 v[2:17], v[178:181], v[152:155], v[2:17]
	s_waitcnt lgkmcnt(5)
	v_mfma_f32_32x32x16_bf16 v[66:81], v[186:189], v[136:139], v[66:81]
	v_mfma_f32_32x32x16_bf16 v[34:49], v[186:189], v[144:147], v[34:49]
	v_mfma_f32_32x32x16_bf16 v[18:33], v[186:189], v[152:155], v[18:33]
	s_setprio 0
	ds_read_b128 v[136:139], v98 offset:36960
	ds_read_b128 v[144:147], v98 offset:41568
	ds_read_b128 v[152:155], v98 offset:46176
	ds_read_b128 v[178:181], v101 offset:96
	ds_read_b128 v[186:189], v101 offset:4704
	s_setprio 1
	s_waitcnt lgkmcnt(6)
	v_mfma_f32_32x32x16_bf16 v[82:97], v[156:159], v[120:123], v[82:97]
	v_mfma_f32_32x32x16_bf16 v[50:65], v[156:159], v[140:143], v[50:65]
	v_mfma_f32_32x32x16_bf16 v[2:17], v[156:159], v[148:151], v[2:17]
	s_waitcnt lgkmcnt(5)
	v_mfma_f32_32x32x16_bf16 v[66:81], v[182:185], v[120:123], v[66:81]
	v_mfma_f32_32x32x16_bf16 v[34:49], v[182:185], v[140:143], v[34:49]
	v_mfma_f32_32x32x16_bf16 v[18:33], v[182:185], v[148:151], v[18:33]
	s_setprio 0
	s_setprio 1
	s_waitcnt lgkmcnt(1)
	v_mfma_f32_32x32x16_bf16 v[82:97], v[178:181], v[136:139], v[82:97]
	v_mfma_f32_32x32x16_bf16 v[50:65], v[178:181], v[144:147], v[50:65]
	v_mfma_f32_32x32x16_bf16 v[2:17], v[178:181], v[152:155], v[2:17]
	s_waitcnt lgkmcnt(0)
	v_mfma_f32_32x32x16_bf16 v[66:81], v[186:189], v[136:139], v[66:81]
	v_mfma_f32_32x32x16_bf16 v[34:49], v[186:189], v[144:147], v[34:49]
	v_mfma_f32_32x32x16_bf16 v[18:33], v[186:189], v[152:155], v[18:33]
	s_setprio 0
	s_barrier
	s_waitcnt vmcnt(4)
	ds_write_b128 v119, v[166:169]
	ds_write_b128 v119, v[162:165] offset:9216
	ds_write_b128 v119, v[106:109] offset:18432
	s_waitcnt vmcnt(2)
	ds_write_b128 v119, v[170:173] offset:27648
	ds_write_b128 v119, v[102:105] offset:36864
	s_waitcnt vmcnt(1)
	ds_write_b128 v119, v[110:113] offset:46080
	s_waitcnt vmcnt(0)
	ds_write_b128 v119, v[174:177] offset:55296
	ds_read_b128 v[102:105], v115 offset:36864
	ds_read_b128 v[106:109], v115 offset:36896
	ds_read_b128 v[110:113], v115 offset:41472
	ds_read_b128 v[120:123], v115 offset:41504
	ds_read_b128 v[136:139], v115 offset:46080
	ds_read_b128 v[140:143], v115 offset:46112
	ds_read_b128 v[144:147], v100
	ds_read_b128 v[148:151], v100 offset:32
	ds_read_b128 v[152:155], v100 offset:4608
	ds_read_b128 v[156:159], v100 offset:4640
	s_setprio 1
	s_waitcnt lgkmcnt(3)
	v_mfma_f32_32x32x16_bf16 v[82:97], v[144:147], v[102:105], v[82:97]
	v_mfma_f32_32x32x16_bf16 v[50:65], v[144:147], v[110:113], v[50:65]
	v_mfma_f32_32x32x16_bf16 v[2:17], v[144:147], v[136:139], v[2:17]
	s_waitcnt lgkmcnt(1)
	v_mfma_f32_32x32x16_bf16 v[66:81], v[152:155], v[102:105], v[66:81]
	v_mfma_f32_32x32x16_bf16 v[34:49], v[152:155], v[110:113], v[34:49]
	v_mfma_f32_32x32x16_bf16 v[18:33], v[152:155], v[136:139], v[18:33]
	s_setprio 0
	ds_read_b128 v[102:105], v115 offset:36928
	ds_read_b128 v[110:113], v115 offset:41536
	ds_read_b128 v[136:139], v115 offset:46144
	ds_read_b128 v[144:147], v100 offset:64
	ds_read_b128 v[152:155], v100 offset:4672
	s_setprio 1
	v_mfma_f32_32x32x16_bf16 v[82:97], v[148:151], v[106:109], v[82:97]
	v_mfma_f32_32x32x16_bf16 v[50:65], v[148:151], v[120:123], v[50:65]
	v_mfma_f32_32x32x16_bf16 v[2:17], v[148:151], v[140:143], v[2:17]
	s_waitcnt lgkmcnt(5)
	v_mfma_f32_32x32x16_bf16 v[66:81], v[156:159], v[106:109], v[66:81]
	v_mfma_f32_32x32x16_bf16 v[34:49], v[156:159], v[120:123], v[34:49]
	v_mfma_f32_32x32x16_bf16 v[18:33], v[156:159], v[140:143], v[18:33]
	s_setprio 0
	ds_read_b128 v[106:109], v115 offset:36960
	ds_read_b128 v[120:123], v115 offset:41568
	ds_read_b128 v[114:117], v115 offset:46176
	ds_read_b128 v[140:143], v100 offset:96
	ds_read_b128 v[148:151], v100 offset:4704
	s_setprio 1
	s_waitcnt lgkmcnt(6)
	v_mfma_f32_32x32x16_bf16 v[82:97], v[144:147], v[102:105], v[82:97]
	v_mfma_f32_32x32x16_bf16 v[50:65], v[144:147], v[110:113], v[50:65]
	v_mfma_f32_32x32x16_bf16 v[2:17], v[144:147], v[136:139], v[2:17]
	s_waitcnt lgkmcnt(5)
	v_mfma_f32_32x32x16_bf16 v[66:81], v[152:155], v[102:105], v[66:81]
	v_mfma_f32_32x32x16_bf16 v[34:49], v[152:155], v[110:113], v[34:49]
	v_mfma_f32_32x32x16_bf16 v[18:33], v[152:155], v[136:139], v[18:33]
	s_setprio 0
	s_setprio 1
	s_waitcnt lgkmcnt(1)
	v_mfma_f32_32x32x16_bf16 v[82:97], v[140:143], v[106:109], v[82:97]
	v_mfma_f32_32x32x16_bf16 v[50:65], v[140:143], v[120:123], v[50:65]
	v_mfma_f32_32x32x16_bf16 v[2:17], v[140:143], v[114:117], v[2:17]
	s_waitcnt lgkmcnt(0)
	v_mfma_f32_32x32x16_bf16 v[66:81], v[148:151], v[106:109], v[66:81]
	v_mfma_f32_32x32x16_bf16 v[34:49], v[148:151], v[120:123], v[34:49]
	v_mfma_f32_32x32x16_bf16 v[18:33], v[148:151], v[114:117], v[18:33]
	s_setprio 0
	s_barrier
	ds_read_b128 v[102:105], v98 offset:36864
	ds_read_b128 v[106:109], v98 offset:36896
	ds_read_b128 v[110:113], v98 offset:41472
	ds_read_b128 v[114:117], v98 offset:41504
	ds_read_b128 v[120:123], v98 offset:46080
	ds_read_b128 v[136:139], v98 offset:46112
	ds_read_b128 v[140:143], v101
	ds_read_b128 v[144:147], v101 offset:32
	ds_read_b128 v[148:151], v101 offset:4608
	ds_read_b128 v[152:155], v101 offset:4640
	s_setprio 1
	s_waitcnt lgkmcnt(3)
	v_mfma_f32_32x32x16_bf16 v[82:97], v[140:143], v[102:105], v[82:97]
	v_mfma_f32_32x32x16_bf16 v[50:65], v[140:143], v[110:113], v[50:65]
	v_mfma_f32_32x32x16_bf16 v[2:17], v[140:143], v[120:123], v[2:17]
	s_waitcnt lgkmcnt(1)
	v_mfma_f32_32x32x16_bf16 v[66:81], v[148:151], v[102:105], v[66:81]
	v_mfma_f32_32x32x16_bf16 v[34:49], v[148:151], v[110:113], v[34:49]
	v_mfma_f32_32x32x16_bf16 v[18:33], v[148:151], v[120:123], v[18:33]
	s_setprio 0
	ds_read_b128 v[102:105], v98 offset:36928
	ds_read_b128 v[110:113], v98 offset:41536
	ds_read_b128 v[120:123], v98 offset:46144
	ds_read_b128 v[140:143], v101 offset:64
	ds_read_b128 v[148:151], v101 offset:4672
	s_setprio 1
	v_mfma_f32_32x32x16_bf16 v[82:97], v[144:147], v[106:109], v[82:97]
	v_mfma_f32_32x32x16_bf16 v[50:65], v[144:147], v[114:117], v[50:65]
	v_mfma_f32_32x32x16_bf16 v[2:17], v[144:147], v[136:139], v[2:17]
	s_waitcnt lgkmcnt(5)
	v_mfma_f32_32x32x16_bf16 v[66:81], v[152:155], v[106:109], v[66:81]
	v_mfma_f32_32x32x16_bf16 v[34:49], v[152:155], v[114:117], v[34:49]
	v_mfma_f32_32x32x16_bf16 v[18:33], v[152:155], v[136:139], v[18:33]
	s_setprio 0
	ds_read_b128 v[106:109], v98 offset:36960
	ds_read_b128 v[114:117], v98 offset:41568
	ds_read_b128 v[136:139], v98 offset:46176
	ds_read_b128 v[144:147], v101 offset:96
	ds_read_b128 v[152:155], v101 offset:4704
	s_setprio 1
	s_waitcnt lgkmcnt(6)
	v_mfma_f32_32x32x16_bf16 v[82:97], v[140:143], v[102:105], v[82:97]
	v_mfma_f32_32x32x16_bf16 v[50:65], v[140:143], v[110:113], v[50:65]
	v_mfma_f32_32x32x16_bf16 v[2:17], v[140:143], v[120:123], v[2:17]
	s_waitcnt lgkmcnt(5)
	v_mfma_f32_32x32x16_bf16 v[66:81], v[148:151], v[102:105], v[66:81]
	v_mfma_f32_32x32x16_bf16 v[34:49], v[148:151], v[110:113], v[34:49]
	v_mfma_f32_32x32x16_bf16 v[18:33], v[148:151], v[120:123], v[18:33]
	s_setprio 0
	s_setprio 1
	s_waitcnt lgkmcnt(1)
	v_mfma_f32_32x32x16_bf16 v[82:97], v[144:147], v[106:109], v[82:97]
	v_mfma_f32_32x32x16_bf16 v[50:65], v[144:147], v[114:117], v[50:65]
	v_mfma_f32_32x32x16_bf16 v[2:17], v[144:147], v[136:139], v[2:17]
	s_waitcnt lgkmcnt(0)
	v_mfma_f32_32x32x16_bf16 v[66:81], v[152:155], v[106:109], v[66:81]
	v_mfma_f32_32x32x16_bf16 v[34:49], v[152:155], v[114:117], v[34:49]
	v_mfma_f32_32x32x16_bf16 v[18:33], v[152:155], v[136:139], v[18:33]
	s_setprio 0
	s_cmp_lt_i32 s9, 43
	s_cselect_b64 s[10:11], -1, 0
	s_and_b32 s3, s8, -4
	s_cmp_eq_u32 s3, 8
	s_cselect_b64 s[8:9], -1, 0
	s_and_b64 s[8:9], s[10:11], s[8:9]
	s_andn2_b64 vcc, exec, s[8:9]
	s_barrier
.LBB0_210:
	v_ashrrev_i32_e32 v98, 6, v118
	v_and_b32_e32 v100, 1, v98
	v_cmp_eq_u32_e32 vcc, 1, v100
	s_movk_i32 s3, 0x2200
	v_mul_lo_u32 v101, v98, s3
	v_cndmask_b32_e32 v100, 0, v125, vcc
	v_add_u32_e32 v108, s6, v100
	v_ashrrev_i32_e32 v100, 1, v118
	v_and_b32_e32 v100, 0xffffffc0, v100
	v_add_u32_e32 v116, s4, v100
	s_movk_i32 s3, 0x3ff
	v_cmp_lt_i32_e64 s[10:11], s3, v116
	v_add_u32_e32 v98, 0xfffff400, v116
	s_movk_i32 s3, 0xf9ff
	v_cmp_lt_u32_e64 s[8:9], s3, v98
	v_subrev_co_u32_e32 v98, vcc, 0xa00, v116
	v_lshrrev_b32_e32 v100, 6, v98
	s_movk_i32 s3, 0x180
	v_mad_u64_u32 v[112:113], s[4:5], v100, s3, 0
	s_movk_i32 s3, 0x800
	v_lshrrev_b32_e32 v100, 3, v118
	v_lshlrev_b32_e32 v102, 2, v118
	v_cmp_gt_u32_e64 s[6:7], s3, v116
	s_mov_b64 s[98:99], s[6:7]
	s_movk_i32 s3, 0x7ff
	v_and_b32_e32 v159, 4, v100
	v_and_b32_e32 v100, 32, v118
	v_and_b32_e32 v155, 60, v102
	v_cmp_lt_u32_e64 s[4:5], s3, v116
	v_lshl_or_b32 v158, v100, 2, v101
	v_lshl_or_b32 v139, v155, 2, v101
	v_cndmask_b32_e64 v101, v128, v129, s[4:5]
	v_add_u32_e32 v102, v101, v116
	v_bfe_u32 v154, v118, 4, 2
	v_lshrrev_b32_e32 v105, 6, v102
	s_movk_i32 s3, 0x6000
	v_and_b32_e32 v161, 31, v118
	v_or_b32_e32 v151, 4, v154
	v_or_b32_e32 v148, 8, v154
	v_or_b32_e32 v146, 12, v154
	v_or_b32_e32 v144, 16, v154
	v_or_b32_e32 v142, 20, v154
	v_or_b32_e32 v138, 24, v154
	v_or_b32_e32 v136, 28, v154
	v_ashrrev_i32_e32 v103, 31, v102
	v_mul_lo_u32 v106, v105, s3
	s_movk_i32 s3, 0x600
	v_mov_b32_e32 v117, v99
	s_xor_b64 s[30:31], vcc, -1
	v_mul_u32_u24_e32 v157, 0x110, v161
	v_mad_u32_u24 v156, v161, s56, v158
	v_lshlrev_b32_e32 v153, 9, v154
	v_mul_u32_u24_e32 v152, 0x110, v154
	v_lshlrev_b32_e32 v150, 9, v151
	v_mad_u32_u24 v149, v154, s56, v126
	v_lshlrev_b32_e32 v147, 9, v148
	v_mad_u32_u24 v141, v154, s56, v127
	v_lshlrev_b32_e32 v145, 9, v146
	v_lshlrev_b32_e32 v143, 9, v144
	v_lshlrev_b32_e32 v140, 9, v142
	v_lshlrev_b32_e32 v137, 9, v138
	v_lshlrev_b32_e32 v135, 9, v136
	v_cndmask_b32_e64 v104, v130, 1.0, s[4:5]
	v_mov_b32_e32 v101, v99
	v_ashrrev_i32_e32 v107, 31, v106
	v_cmp_gt_u32_e32 vcc, s3, v116
	v_lshl_add_u64 v[110:111], v[102:103], 1, s[20:21]
	v_lshl_add_u64 v[114:115], v[116:117], 1, s[96:97]
	v_or_b32_e32 v118, v108, v161
	s_and_saveexec_b64 s[12:13], s[10:11]
	s_xor_b64 s[34:35], exec, s[12:13]
	s_cbranch_execz .LBB0_266
	s_and_saveexec_b64 s[12:13], s[8:9]
	s_xor_b64 s[36:37], exec, s[12:13]
	s_cbranch_execz .LBB0_263
	v_cmp_gt_i32_e64 s[12:13], s57, v108
	s_and_saveexec_b64 s[14:15], s[30:31]
	s_xor_b64 s[38:39], exec, s[14:15]
	s_cbranch_execz .LBB0_231
	v_ashrrev_i32_e32 v120, 6, v108
	v_ashrrev_i32_e32 v121, 31, v120
	v_lshl_add_u64 v[120:121], v[112:113], 0, v[120:121]
	v_lshlrev_b64 v[120:121], 6, v[120:121]
	v_and_b32_e32 v105, 63, v118
	v_lshlrev_b32_e32 v118, 1, v105
	v_mov_b32_e32 v119, v99
	v_or3_b32 v122, v120, v159, 32
	v_mov_b32_e32 v123, v121
	v_lshl_add_u64 v[118:119], s[24:25], 0, v[118:119]
	v_lshlrev_b64 v[122:123], 7, v[122:123]
	v_cvt_pk_bf16_f32 v105, v82, v83
	v_lshl_add_u64 v[122:123], v[118:119], 0, v[122:123]
	v_cvt_pk_bf16_f32 v109, v84, v85
	global_store_short v[122:123], v105, off offset:-4096
	global_store_short_d16_hi v[122:123], v105, off offset:-3968
	v_cvt_pk_bf16_f32 v117, v86, v87
	global_store_short v[122:123], v109, off offset:-3840
	global_store_short_d16_hi v[122:123], v109, off offset:-3712
	v_cvt_pk_bf16_f32 v162, v88, v89
	global_store_short v[122:123], v117, off offset:-3072
	global_store_short_d16_hi v[122:123], v117, off offset:-2944
	v_cvt_pk_bf16_f32 v163, v90, v91
	global_store_short v[122:123], v162, off offset:-2816
	global_store_short_d16_hi v[122:123], v162, off offset:-2688
	v_cvt_pk_bf16_f32 v164, v92, v93
	global_store_short v[122:123], v163, off offset:-2048
	global_store_short_d16_hi v[122:123], v163, off offset:-1920
	v_cvt_pk_bf16_f32 v165, v94, v95
	global_store_short v[122:123], v164, off offset:-1792
	global_store_short_d16_hi v[122:123], v164, off offset:-1664
	v_cvt_pk_bf16_f32 v166, v96, v97
	global_store_short v[122:123], v165, off offset:-1024
	global_store_short_d16_hi v[122:123], v165, off offset:-896
	v_cvt_pk_bf16_f32 v167, v66, v67
	global_store_short v[122:123], v166, off offset:-768
	global_store_short_d16_hi v[122:123], v166, off offset:-640
	v_cvt_pk_bf16_f32 v168, v68, v69
	global_store_short v[122:123], v167, off
	global_store_short_d16_hi v[122:123], v167, off offset:128
	v_cvt_pk_bf16_f32 v169, v70, v71
	global_store_short v[122:123], v168, off offset:256
	global_store_short_d16_hi v[122:123], v168, off offset:384
	v_cvt_pk_bf16_f32 v170, v72, v73
	global_store_short v[122:123], v169, off offset:1024
	global_store_short_d16_hi v[122:123], v169, off offset:1152
	v_cvt_pk_bf16_f32 v171, v74, v75
	global_store_short v[122:123], v170, off offset:1280
	global_store_short_d16_hi v[122:123], v170, off offset:1408
	v_cvt_pk_bf16_f32 v172, v76, v77
	global_store_short v[122:123], v171, off offset:2048
	global_store_short_d16_hi v[122:123], v171, off offset:2176
	v_cvt_pk_bf16_f32 v173, v78, v79
	global_store_short v[122:123], v172, off offset:2304
	global_store_short_d16_hi v[122:123], v172, off offset:2432
	v_cvt_pk_bf16_f32 v174, v80, v81
	global_store_short v[122:123], v173, off offset:3072
	global_store_short_d16_hi v[122:123], v173, off offset:3200
	global_store_short v[122:123], v174, off offset:3328
	global_store_short_d16_hi v[122:123], v174, off offset:3456
	s_and_saveexec_b64 s[40:41], s[12:13]
	s_cbranch_execz .LBB0_230
	v_permlane32_swap_b32_e32 v82, v66
	v_permlane32_swap_b32_e32 v83, v67
	v_permlane32_swap_b32_e32 v84, v68
	v_permlane32_swap_b32_e32 v85, v69
	v_ashrrev_i32_e32 v109, 31, v108
	v_permlane32_swap_b32_e32 v86, v70
	v_permlane32_swap_b32_e32 v87, v71
	v_permlane32_swap_b32_e32 v88, v72
	v_permlane32_swap_b32_e32 v89, v73
	v_permlane32_swap_b32_e32 v90, v74
	v_permlane32_swap_b32_e32 v91, v75
	v_permlane32_swap_b32_e32 v92, v76
	v_permlane32_swap_b32_e32 v93, v77
	v_permlane32_swap_b32_e32 v94, v78
	v_permlane32_swap_b32_e32 v95, v79
	v_permlane32_swap_b32_e32 v96, v80
	v_permlane32_swap_b32_e32 v97, v81
	ds_write_b128 v156, v[82:85]
	ds_write_b128 v156, v[66:69] offset:16
	ds_write_b128 v156, v[86:89] offset:32
	ds_write_b128 v156, v[70:73] offset:48
	ds_write_b128 v156, v[90:93] offset:64
	ds_write_b128 v156, v[74:77] offset:80
	ds_write_b128 v156, v[94:97] offset:96
	ds_write_b128 v156, v[78:81] offset:112
	v_lshlrev_b64 v[66:67], 11, v[108:109]
	v_lshl_add_u64 v[66:67], s[26:27], 0, v[66:67]
	v_lshl_add_u64 v[66:67], v[98:99], 2, v[66:67]
	v_lshlrev_b32_e32 v68, 2, v155
	v_mov_b32_e32 v69, v99
	v_lshl_add_u64 v[66:67], v[66:67], 0, v[68:69]
	v_or_b32_e32 v68, v108, v154
	v_cmp_gt_i32_e64 s[14:15], s57, v68
	s_and_saveexec_b64 s[42:43], s[14:15]
	s_cbranch_execz .LBB0_216
	v_lshlrev_b32_e32 v68, 2, v153
	v_mov_b32_e32 v69, v99
	v_lshl_add_u64 v[72:73], v[66:67], 0, v[68:69]
	v_add_u32_e32 v68, v139, v152
	ds_read_b128 v[68:71], v68
	s_waitcnt lgkmcnt(0)
	global_store_dwordx4 v[72:73], v[68:71], off

.LBB0_238:
	s_or_b64 exec, exec, s[14:15]
	v_pk_mul_f32 v[82:83], v[104:105], v[82:83] op_sel_hi:[0,1]
	v_pk_mul_f32 v[84:85], v[104:105], v[84:85] op_sel_hi:[0,1]
	v_pk_mul_f32 v[66:67], v[104:105], v[66:67] op_sel_hi:[0,1]
	v_lshlrev_b32_e32 v162, 1, v100
	v_mov_b32_e32 v163, v99
	v_cvt_pk_bf16_f32 v82, v82, v83
	v_cvt_pk_bf16_f32 v83, v84, v85
	v_cvt_pk_bf16_f32 v84, v66, v67
	v_pk_mul_f32 v[66:67], v[104:105], v[68:69] op_sel_hi:[0,1]
	v_lshl_add_u64 v[122:123], v[122:123], 0, v[162:163]
	v_cvt_pk_bf16_f32 v85, v66, v67
	ds_write_b128 v202, v[82:85]
	global_load_dwordx4 v[66:69], v[120:121], off offset:32
	s_nop 0
	global_load_dwordx4 v[82:85], v[120:121], off offset:48
	v_mov_b32_e32 v119, v118
	v_pk_mul_f32 v[86:87], v[118:119], v[86:87]
	v_pk_mul_f32 v[88:89], v[118:119], v[88:89]
	v_pk_mul_f32 v[162:163], v[118:119], v[70:71]
	v_pk_mul_f32 v[164:165], v[118:119], v[72:73]
	s_waitcnt vmcnt(1)
	v_pk_mul_f32 v[70:71], v[86:87], v[66:67]
	v_pk_mul_f32 v[72:73], v[88:89], v[68:69]
	s_waitcnt vmcnt(0)
	v_pk_mul_f32 v[66:67], v[162:163], v[82:83]
	v_pk_mul_f32 v[68:69], v[164:165], v[84:85]
	s_and_saveexec_b64 s[14:15], s[40:41]
	s_cbranch_execz .LBB0_240
	v_add_u32_e32 v82, v158, v157
	ds_write_b128 v82, v[70:73] offset:32
	ds_write_b128 v82, v[66:69] offset:48
.LBB0_240:
	s_or_b64 exec, exec, s[14:15]
	v_mov_b32_e32 v105, v104
	v_pk_mul_f32 v[70:71], v[104:105], v[70:71]
	v_pk_mul_f32 v[72:73], v[104:105], v[72:73]
	v_pk_mul_f32 v[66:67], v[104:105], v[66:67]
	v_cvt_pk_bf16_f32 v70, v70, v71
	v_cvt_pk_bf16_f32 v71, v72, v73
	v_cvt_pk_bf16_f32 v72, v66, v67
	v_pk_mul_f32 v[66:67], v[104:105], v[68:69]
	v_pk_mul_f32 v[74:75], v[118:119], v[74:75]
	v_cvt_pk_bf16_f32 v73, v66, v67
	ds_write_b128 v202, v[70:73] offset:16
	global_load_dwordx4 v[66:69], v[120:121], off offset:64
	global_load_dwordx4 v[82:85], v[120:121], off offset:80
	v_pk_mul_f32 v[70:71], v[118:119], v[90:91]
	v_pk_mul_f32 v[72:73], v[118:119], v[92:93]
	v_pk_mul_f32 v[76:77], v[118:119], v[76:77]
	s_waitcnt vmcnt(1)
	v_pk_mul_f32 v[70:71], v[70:71], v[66:67]
	v_pk_mul_f32 v[72:73], v[72:73], v[68:69]
	s_waitcnt vmcnt(0)
	v_pk_mul_f32 v[66:67], v[74:75], v[82:83]
	v_pk_mul_f32 v[68:69], v[76:77], v[84:85]
	s_and_saveexec_b64 s[14:15], s[40:41]
	s_cbranch_execz .LBB0_242
	v_add_u32_e32 v74, v158, v157
	ds_write_b128 v74, v[70:73] offset:64
	ds_write_b128 v74, v[66:69] offset:80
.LBB0_242:
	s_or_b64 exec, exec, s[14:15]
	v_pk_mul_f32 v[70:71], v[104:105], v[70:71]
	v_pk_mul_f32 v[72:73], v[104:105], v[72:73]
	v_pk_mul_f32 v[66:67], v[104:105], v[66:67]
	v_cvt_pk_bf16_f32 v70, v70, v71
	v_cvt_pk_bf16_f32 v71, v72, v73
	v_cvt_pk_bf16_f32 v72, v66, v67
	v_pk_mul_f32 v[66:67], v[104:105], v[68:69]
	v_pk_mul_f32 v[78:79], v[118:119], v[78:79]
	v_cvt_pk_bf16_f32 v73, v66, v67
	ds_write_b128 v202, v[70:73] offset:32
	global_load_dwordx4 v[66:69], v[120:121], off offset:96
	global_load_dwordx4 v[74:77], v[120:121], off offset:112
	v_pk_mul_f32 v[70:71], v[118:119], v[94:95]
	v_pk_mul_f32 v[72:73], v[118:119], v[96:97]
	v_pk_mul_f32 v[80:81], v[118:119], v[80:81]
	s_waitcnt vmcnt(1)
	v_pk_mul_f32 v[70:71], v[70:71], v[66:67]
	v_pk_mul_f32 v[72:73], v[72:73], v[68:69]
	s_waitcnt vmcnt(0)
	v_pk_mul_f32 v[66:67], v[78:79], v[74:75]
	v_pk_mul_f32 v[68:69], v[80:81], v[76:77]
	s_and_saveexec_b64 s[14:15], s[40:41]
	s_cbranch_execz .LBB0_244
	v_add_u32_e32 v74, v158, v157
	ds_write_b128 v74, v[70:73] offset:96
	ds_write_b128 v74, v[66:69] offset:112
.LBB0_244:
	s_or_b64 exec, exec, s[14:15]
	v_pk_mul_f32 v[70:71], v[104:105], v[70:71]
	v_pk_mul_f32 v[72:73], v[104:105], v[72:73]
	v_pk_mul_f32 v[66:67], v[104:105], v[66:67]
	v_cvt_pk_bf16_f32 v70, v70, v71
	v_cvt_pk_bf16_f32 v71, v72, v73
	v_cvt_pk_bf16_f32 v72, v66, v67
	v_pk_mul_f32 v[66:67], v[104:105], v[68:69]
	s_and_b64 s[12:13], s[4:5], s[12:13]
	v_cvt_pk_bf16_f32 v73, v66, v67
	ds_write_b128 v202, v[70:73] offset:48
	ds_read_b128 v[176:179], v204
	ds_read_b128 v[180:183], v204 offset:144
	ds_read_b128 v[184:187], v204 offset:288
	ds_read_b128 v[188:191], v204 offset:432
	s_cmp_lg_u64 s[98:99], 0
	s_cbranch_scc0 .Lg1co_k0
	v_lshl_add_u64 v[192:193], v[122:123], 0, v[206:207]
	s_waitcnt lgkmcnt(3)
	global_store_dwordx4 v[192:193], v[176:179], off
	s_waitcnt lgkmcnt(2)
	global_store_dwordx4 v[192:193], v[180:183], off offset:1024
	s_waitcnt lgkmcnt(1)
	global_store_dwordx4 v[192:193], v[184:187], off offset:2048
	s_waitcnt lgkmcnt(0)
	global_store_dwordx4 v[192:193], v[188:191], off offset:3072
	s_branch .Lg1co_e0
.Lg1co_k0:
	v_lshl_add_u64 v[192:193], v[122:123], 0, v[208:209]
	s_waitcnt lgkmcnt(3)
	global_store_dwordx4 v[192:193], v[176:179], off
	s_waitcnt lgkmcnt(2)
	global_store_dwordx4 v[192:193], v[180:183], off offset:128
	s_waitcnt lgkmcnt(1)
	global_store_dwordx4 v[192:193], v[184:187], off offset:256
	s_waitcnt lgkmcnt(0)
	global_store_dwordx4 v[192:193], v[188:191], off offset:384
.Lg1co_e0:
	s_and_saveexec_b64 s[14:15], s[12:13]
	s_cbranch_execz .LBB0_261
	v_ashrrev_i32_e32 v109, 31, v108
	v_lshlrev_b64 v[66:67], 11, v[108:109]
	v_lshl_add_u64 v[66:67], s[28:29], 0, v[66:67]
	v_lshl_add_u64 v[66:67], v[102:103], 2, v[66:67]
	v_lshlrev_b32_e32 v68, 2, v155
	v_mov_b32_e32 v69, v99
	v_lshl_add_u64 v[66:67], v[66:67], 0, v[68:69]
	v_or_b32_e32 v68, v108, v154
	v_cmp_gt_i32_e64 s[12:13], s57, v68
	s_and_saveexec_b64 s[40:41], s[12:13]
	s_cbranch_execz .LBB0_247
	v_add_u32_e32 v68, v139, v152
	ds_read_b128 v[68:71], v68
	v_lshlrev_b32_e32 v72, 2, v153
	v_mov_b32_e32 v73, v99
	v_lshl_add_u64 v[72:73], v[66:67], 0, v[72:73]
	s_waitcnt lgkmcnt(0)
	global_store_dwordx4 v[72:73], v[68:71], off

.LBB0_263:
	s_andn2_saveexec_b64 s[12:13], s[36:37]
	s_cbranch_execz .LBB0_265
	v_mul_f32_e32 v105, 0xbfb8aa3b, v82
	v_mul_f32_e32 v109, 0xbfb8aa3b, v66
	v_mul_f32_e32 v117, 0xbfb8aa3b, v83
	v_exp_f32_e32 v105, v105
	v_exp_f32_e32 v109, v109
	v_exp_f32_e32 v117, v117
	v_ashrrev_i32_e32 v119, 31, v118
	v_add_f32_e32 v105, 1.0, v105
	v_add_f32_e32 v109, 1.0, v109
	v_add_f32_e32 v117, 1.0, v117
	v_rcp_f32_e32 v105, v105
	v_rcp_f32_e32 v109, v109
	v_rcp_f32_e32 v117, v117
	v_lshlrev_b64 v[118:119], 10, v[118:119]
	v_lshl_add_u64 v[118:119], v[114:115], 0, v[118:119]
	v_cndmask_b32_e32 v120, v133, v134, vcc
	v_mov_b32_e32 v121, v99
	v_lshl_add_u64 v[118:119], v[118:119], 0, v[120:121]
	v_mul_f32_e32 v120, 0xbfb8aa3b, v67
	v_mul_f32_e32 v82, v82, v105
	v_mul_f32_e32 v105, v66, v109
	v_mul_f32_e32 v83, v83, v117
	v_mul_f32_e32 v109, 0xbfb8aa3b, v84
	v_mul_f32_e32 v117, 0xbfb8aa3b, v68
	v_exp_f32_e32 v120, v120
	v_exp_f32_e32 v109, v109
	v_exp_f32_e32 v117, v117
	v_permlane32_swap_b32_e32 v82, v105
	v_add_f32_e32 v66, 1.0, v120
	v_add_f32_e32 v109, 1.0, v109
	v_add_f32_e32 v117, 1.0, v117
	v_rcp_f32_e32 v66, v66
	v_rcp_f32_e32 v109, v109
	v_rcp_f32_e32 v117, v117
	v_mul_f32_e32 v120, 0xbfb8aa3b, v85
	v_mul_f32_e32 v121, v67, v66
	v_mul_f32_e32 v84, v84, v109
	v_mul_f32_e32 v109, v68, v117
	v_mul_f32_e32 v67, 0xbfb8aa3b, v69
	v_mul_f32_e32 v68, 0xbfb8aa3b, v86
	v_exp_f32_e32 v67, v67
	v_exp_f32_e32 v68, v68
	v_exp_f32_e32 v120, v120
	v_mul_f32_e32 v117, 0xbfb8aa3b, v70
	v_add_f32_e32 v67, 1.0, v67
	v_add_f32_e32 v68, 1.0, v68
	v_rcp_f32_e32 v67, v67
	v_rcp_f32_e32 v68, v68
	v_add_f32_e32 v66, 1.0, v120
	v_rcp_f32_e32 v66, v66
	v_mul_f32_e32 v69, v69, v67
	v_mul_f32_e32 v86, v86, v68
	v_mul_f32_e32 v67, 0xbfb8aa3b, v87
	v_mul_f32_e32 v68, 0xbfb8aa3b, v71
	v_exp_f32_e32 v67, v67
	v_exp_f32_e32 v68, v68
	v_exp_f32_e32 v117, v117
	v_mul_f32_e32 v85, v85, v66
	v_add_f32_e32 v67, 1.0, v67
	v_add_f32_e32 v68, 1.0, v68
	v_rcp_f32_e32 v67, v67
	v_rcp_f32_e32 v68, v68
	v_add_f32_e32 v66, 1.0, v117
	v_mul_f32_e32 v117, 0xbfb8aa3b, v88
	v_mul_f32_e32 v87, v87, v67
	v_mul_f32_e32 v122, v71, v68
	v_mul_f32_e32 v67, 0xbfb8aa3b, v72
	v_mul_f32_e32 v68, 0xbfb8aa3b, v89
	v_exp_f32_e32 v67, v67
	v_exp_f32_e32 v68, v68
	v_rcp_f32_e32 v66, v66
	v_exp_f32_e32 v117, v117
	v_add_f32_e32 v67, 1.0, v67
	v_add_f32_e32 v68, 1.0, v68
	v_rcp_f32_e32 v67, v67
	v_rcp_f32_e32 v68, v68
	v_mul_f32_e32 v120, v70, v66
	v_add_f32_e32 v66, 1.0, v117
	v_mul_f32_e32 v72, v72, v67
	v_mul_f32_e32 v89, v89, v68
	v_mul_f32_e32 v67, 0xbfb8aa3b, v90
	v_mul_f32_e32 v68, 0xbfb8aa3b, v74
	v_exp_f32_e32 v67, v67
	v_exp_f32_e32 v68, v68
	v_mul_f32_e32 v70, 0xbfb8aa3b, v73
	v_rcp_f32_e32 v66, v66
	v_add_f32_e32 v67, 1.0, v67
	v_add_f32_e32 v68, 1.0, v68
	v_rcp_f32_e32 v67, v67
	v_rcp_f32_e32 v68, v68
	v_exp_f32_e32 v70, v70
	v_mul_f32_e32 v88, v88, v66
	v_mul_f32_e32 v90, v90, v67
	v_mul_f32_e32 v74, v74, v68
	v_mul_f32_e32 v67, 0xbfb8aa3b, v75
	v_mul_f32_e32 v68, 0xbfb8aa3b, v92
	v_exp_f32_e32 v67, v67
	v_exp_f32_e32 v68, v68
	v_add_f32_e32 v66, 1.0, v70
	v_mul_f32_e32 v70, 0xbfb8aa3b, v91
	v_add_f32_e32 v67, 1.0, v67
	v_add_f32_e32 v68, 1.0, v68
	v_rcp_f32_e32 v67, v67
	v_rcp_f32_e32 v68, v68
	v_rcp_f32_e32 v66, v66
	v_exp_f32_e32 v70, v70
	v_mul_f32_e32 v75, v75, v67
	v_mul_f32_e32 v92, v92, v68
	v_mul_f32_e32 v67, 0xbfb8aa3b, v93
	v_mul_f32_e32 v68, 0xbfb8aa3b, v77
	v_exp_f32_e32 v67, v67
	v_exp_f32_e32 v68, v68
	v_mul_f32_e32 v73, v73, v66
	v_add_f32_e32 v66, 1.0, v70
	v_mul_f32_e32 v70, 0xbfb8aa3b, v76
	v_add_f32_e32 v67, 1.0, v67
	v_add_f32_e32 v68, 1.0, v68
	v_rcp_f32_e32 v66, v66
	v_exp_f32_e32 v70, v70
	v_rcp_f32_e32 v67, v67
	v_rcp_f32_e32 v68, v68
	v_mul_f32_e32 v91, v91, v66
	v_add_f32_e32 v66, 1.0, v70
	v_mul_f32_e32 v70, 0xbfb8aa3b, v94
	v_mul_f32_e32 v93, v93, v67
	v_mul_f32_e32 v77, v77, v68
	v_mul_f32_e32 v67, 0xbfb8aa3b, v78
	v_mul_f32_e32 v68, 0xbfb8aa3b, v95
	v_rcp_f32_e32 v66, v66
	v_exp_f32_e32 v70, v70
	v_exp_f32_e32 v67, v67
	v_exp_f32_e32 v68, v68
	v_mul_f32_e32 v76, v76, v66
	v_add_f32_e32 v66, 1.0, v70
	v_add_f32_e32 v67, 1.0, v67
	v_add_f32_e32 v68, 1.0, v68
	v_mul_f32_e32 v70, 0xbfb8aa3b, v79
	v_rcp_f32_e32 v66, v66
	v_rcp_f32_e32 v67, v67
	v_rcp_f32_e32 v68, v68
	v_exp_f32_e32 v70, v70
	v_mul_f32_e32 v94, v94, v66
	v_mul_f32_e32 v78, v78, v67
	v_mul_f32_e32 v95, v95, v68
	v_add_f32_e32 v66, 1.0, v70
	v_mul_f32_e32 v67, 0xbfb8aa3b, v96
	v_mul_f32_e32 v68, 0xbfb8aa3b, v80
	v_rcp_f32_e32 v66, v66
	v_exp_f32_e32 v67, v67
	v_exp_f32_e32 v68, v68
	v_mul_f32_e32 v70, 0xbfb8aa3b, v81
	v_mul_f32_e32 v79, v79, v66
	v_add_f32_e32 v66, 1.0, v67
	v_add_f32_e32 v67, 1.0, v68
	v_mul_f32_e32 v68, 0xbfb8aa3b, v97
	v_exp_f32_e32 v68, v68
	v_exp_f32_e32 v70, v70
	v_rcp_f32_e32 v66, v66
	v_rcp_f32_e32 v67, v67
	v_add_f32_e32 v68, 1.0, v68
	v_add_f32_e32 v70, 1.0, v70
	v_rcp_f32_e32 v68, v68
	v_rcp_f32_e32 v70, v70
	v_mul_f32_e32 v96, v96, v66
	v_mul_f32_e32 v80, v80, v67
	v_permlane32_swap_b32_e32 v83, v121
	v_permlane32_swap_b32_e32 v84, v109
	v_permlane32_swap_b32_e32 v85, v69
	v_lshlrev_b32_e32 v66, 1, v100
	v_mov_b32_e32 v67, v99
	v_mul_f32_e32 v97, v97, v68
	v_mul_f32_e32 v81, v81, v70
	v_permlane32_swap_b32_e32 v86, v120
	v_permlane32_swap_b32_e32 v87, v122
	v_permlane32_swap_b32_e32 v88, v72
	v_permlane32_swap_b32_e32 v89, v73
	v_lshl_add_u64 v[70:71], v[118:119], 0, v[66:67]
	v_cvt_pk_bf16_f32 v66, v82, v83
	v_cvt_pk_bf16_f32 v67, v84, v85
	v_cvt_pk_bf16_f32 v68, v105, v121
	v_cvt_pk_bf16_f32 v69, v109, v69
	v_permlane32_swap_b32_e32 v90, v74
	v_permlane32_swap_b32_e32 v91, v75
	v_permlane32_swap_b32_e32 v92, v76
	v_permlane32_swap_b32_e32 v93, v77
	ds_write_b128 v202, v[66:69]
	v_permlane32_swap_b32_e32 v94, v78
	s_nop 0
	v_cvt_pk_bf16_f32 v66, v86, v87
	v_cvt_pk_bf16_f32 v67, v88, v89
	v_cvt_pk_bf16_f32 v68, v120, v122
	v_cvt_pk_bf16_f32 v69, v72, v73
	v_permlane32_swap_b32_e32 v95, v79
	v_permlane32_swap_b32_e32 v96, v80
	v_permlane32_swap_b32_e32 v97, v81
	ds_write_b128 v202, v[66:69] offset:16
	s_nop 1
	v_cvt_pk_bf16_f32 v66, v90, v91
	v_cvt_pk_bf16_f32 v67, v92, v93
	v_cvt_pk_bf16_f32 v68, v74, v75
	v_cvt_pk_bf16_f32 v69, v76, v77
	ds_write_b128 v202, v[66:69] offset:32
	s_nop 1
	v_cvt_pk_bf16_f32 v66, v94, v95
	v_cvt_pk_bf16_f32 v67, v96, v97
	v_cvt_pk_bf16_f32 v68, v78, v79
	v_cvt_pk_bf16_f32 v69, v80, v81
	ds_write_b128 v202, v[66:69] offset:48
	v_lshl_add_u64 v[192:193], v[70:71], 0, v[206:207]
	ds_read_b128 v[176:179], v204
	ds_read_b128 v[180:183], v204 offset:144
	ds_read_b128 v[184:187], v204 offset:288
	ds_read_b128 v[188:191], v204 offset:432
	s_waitcnt lgkmcnt(3)
	global_store_dwordx4 v[192:193], v[176:179], off
	s_waitcnt lgkmcnt(2)
	global_store_dwordx4 v[192:193], v[180:183], off offset:1024
	s_waitcnt lgkmcnt(1)
	global_store_dwordx4 v[192:193], v[184:187], off offset:2048
	s_waitcnt lgkmcnt(0)
	global_store_dwordx4 v[192:193], v[188:191], off offset:3072

.LBB0_266:
	s_or_saveexec_b64 s[14:15], s[34:35]
	v_ashrrev_i32_e32 v116, 1, v116
	v_ashrrev_i32_e32 v117, 31, v116
	v_lshl_add_u64 v[116:117], v[116:117], 1, s[18:19]
	v_lshl_add_u64 v[116:117], v[116:117], 0, v[100:101]
	s_xor_b64 exec, exec, s[14:15]
	s_cbranch_execz .LBB0_268
	v_mul_f32_e32 v66, 0xbfb8aa3b, v66
	v_mul_f32_e32 v67, 0xbfb8aa3b, v67
	v_exp_f32_e32 v66, v66
	v_exp_f32_e32 v67, v67
	v_mul_f32_e32 v68, 0xbfb8aa3b, v68
	v_exp_f32_e32 v68, v68
	v_add_f32_e32 v66, 1.0, v66
	v_add_f32_e32 v67, 1.0, v67
	v_rcp_f32_e32 v66, v66
	v_rcp_f32_e32 v67, v67
	v_cmp_gt_i32_e64 s[12:13], s57, v118
	v_mul_f32_e32 v82, v82, v66
	v_mul_f32_e32 v83, v83, v67
	v_add_f32_e32 v66, 1.0, v68
	v_mul_f32_e32 v67, 0xbfb8aa3b, v69
	v_mul_f32_e32 v68, 0xbfb8aa3b, v70
	v_exp_f32_e32 v67, v67
	v_exp_f32_e32 v68, v68
	v_mul_f32_e32 v69, 0xbfb8aa3b, v71
	v_rcp_f32_e32 v66, v66
	v_add_f32_e32 v67, 1.0, v67
	v_add_f32_e32 v68, 1.0, v68
	v_rcp_f32_e32 v67, v67
	v_rcp_f32_e32 v68, v68
	v_exp_f32_e32 v69, v69
	v_mul_f32_e32 v84, v84, v66
	v_mul_f32_e32 v85, v85, v67
	v_mul_f32_e32 v86, v86, v68
	v_mul_f32_e32 v67, 0xbfb8aa3b, v72
	v_mul_f32_e32 v68, 0xbfb8aa3b, v73
	v_exp_f32_e32 v67, v67
	v_exp_f32_e32 v68, v68
	v_add_f32_e32 v66, 1.0, v69
	v_mul_f32_e32 v69, 0xbfb8aa3b, v74
	v_add_f32_e32 v67, 1.0, v67
	v_add_f32_e32 v68, 1.0, v68
	v_rcp_f32_e32 v67, v67
	v_rcp_f32_e32 v68, v68
	v_rcp_f32_e32 v66, v66
	v_exp_f32_e32 v69, v69
	v_mul_f32_e32 v73, v88, v67
	v_mul_f32_e32 v74, v89, v68
	v_mul_f32_e32 v67, 0xbfb8aa3b, v75
	v_mul_f32_e32 v68, 0xbfb8aa3b, v76
	v_exp_f32_e32 v67, v67
	v_exp_f32_e32 v68, v68
	v_mul_f32_e32 v72, v87, v66
	v_add_f32_e32 v66, 1.0, v69
	v_add_f32_e32 v67, 1.0, v67
	v_add_f32_e32 v68, 1.0, v68
	v_mul_f32_e32 v69, 0xbfb8aa3b, v77
	v_rcp_f32_e32 v66, v66
	v_rcp_f32_e32 v67, v67
	v_rcp_f32_e32 v68, v68
	v_exp_f32_e32 v69, v69
	v_mul_f32_e32 v75, v90, v66
	v_mul_f32_e32 v76, v91, v67
	v_mul_f32_e32 v77, v92, v68
	v_add_f32_e32 v66, 1.0, v69
	v_mul_f32_e32 v67, 0xbfb8aa3b, v78
	v_mul_f32_e32 v68, 0xbfb8aa3b, v79
	v_rcp_f32_e32 v66, v66
	v_exp_f32_e32 v67, v67
	v_exp_f32_e32 v68, v68
	v_mul_f32_e32 v70, 0xbfb8aa3b, v81
	v_mul_f32_e32 v69, v93, v66
	v_add_f32_e32 v66, 1.0, v67
	v_add_f32_e32 v67, 1.0, v68
	v_rcp_f32_e32 v67, v67
	v_mul_f32_e32 v68, 0xbfb8aa3b, v80
	v_rcp_f32_e32 v66, v66
	v_exp_f32_e32 v68, v68
	v_exp_f32_e32 v70, v70
	v_mul_f32_e32 v79, v95, v67
	v_add_u32_e32 v67, 0xffffe000, v108
	v_lshrrev_b32_e32 v67, 12, v67
	v_add_f32_e32 v68, 1.0, v68
	v_add_f32_e32 v70, 1.0, v70
	v_mul_f32_e32 v78, v94, v66
	v_ashrrev_i32_e32 v66, 8, v108
	v_add_u32_e32 v67, 32, v67
	v_rcp_f32_e32 v68, v68
	v_rcp_f32_e32 v70, v70
	v_cndmask_b32_e64 v66, v67, v66, s[12:13]
	v_lshlrev_b32_e32 v66, 5, v66
	v_add3_u32 v66, v118, v66, 16
	v_ashrrev_i32_e32 v67, 31, v66
	v_mul_f32_e32 v80, v96, v68
	v_mul_f32_e32 v81, v97, v70
	v_permlane32_swap_b32_e32 v82, v75
	v_permlane32_swap_b32_e32 v83, v76
	v_permlane32_swap_b32_e32 v84, v77
	v_permlane32_swap_b32_e32 v85, v69
	v_lshlrev_b64 v[66:67], 10, v[66:67]
	v_permlane32_swap_b32_e32 v86, v78
	v_permlane32_swap_b32_e32 v72, v79
	v_permlane32_swap_b32_e32 v73, v80
	v_permlane32_swap_b32_e32 v74, v81
	v_lshl_add_u64 v[70:71], v[116:117], 0, v[66:67]
	v_cvt_pk_bf16_f32 v66, v82, v83
	v_cvt_pk_bf16_f32 v67, v84, v85
	v_cvt_pk_bf16_f32 v68, v75, v76
	v_cvt_pk_bf16_f32 v69, v77, v69
	ds_write_b128 v203, v[66:69]
	s_nop 1
	v_cvt_pk_bf16_f32 v66, v86, v72
	v_cvt_pk_bf16_f32 v67, v73, v74
	v_cvt_pk_bf16_f32 v68, v78, v79
	v_cvt_pk_bf16_f32 v69, v80, v81
	ds_write_b128 v203, v[66:69] offset:16
	v_lshl_add_u64 v[192:193], v[70:71], 0, v[210:211]
	ds_read_b128 v[176:179], v205
	ds_read_b128 v[180:183], v205 offset:144
	s_waitcnt lgkmcnt(1)
	global_store_dwordx4 v[192:193], v[176:179], off
	s_waitcnt lgkmcnt(0)
	global_store_dwordx4 v[192:193], v[180:183], off offset:1024

.LBB0_296:
	s_or_b64 exec, exec, s[14:15]
	v_pk_mul_f32 v[50:51], v[104:105], v[50:51] op_sel_hi:[0,1]
	v_pk_mul_f32 v[52:53], v[104:105], v[52:53] op_sel_hi:[0,1]
	v_pk_mul_f32 v[34:35], v[104:105], v[34:35] op_sel_hi:[0,1]
	v_lshlrev_b32_e32 v74, 1, v100
	v_mov_b32_e32 v75, v99
	v_cvt_pk_bf16_f32 v50, v50, v51
	v_cvt_pk_bf16_f32 v51, v52, v53
	v_cvt_pk_bf16_f32 v52, v34, v35
	v_pk_mul_f32 v[34:35], v[104:105], v[36:37] op_sel_hi:[0,1]
	v_lshl_add_u64 v[72:73], v[72:73], 0, v[74:75]
	v_cvt_pk_bf16_f32 v53, v34, v35
	ds_write_b128 v202, v[50:53]
	global_load_dwordx4 v[34:37], v[70:71], off offset:32
	s_nop 0
	global_load_dwordx4 v[50:53], v[70:71], off offset:48
	v_mov_b32_e32 v69, v68
	v_pk_mul_f32 v[54:55], v[68:69], v[54:55]
	v_pk_mul_f32 v[56:57], v[68:69], v[56:57]
	v_pk_mul_f32 v[74:75], v[68:69], v[38:39]
	v_pk_mul_f32 v[76:77], v[68:69], v[40:41]
	s_waitcnt vmcnt(1)
	v_pk_mul_f32 v[38:39], v[54:55], v[34:35]
	v_pk_mul_f32 v[40:41], v[56:57], v[36:37]
	s_waitcnt vmcnt(0)
	v_pk_mul_f32 v[34:35], v[74:75], v[50:51]
	v_pk_mul_f32 v[36:37], v[76:77], v[52:53]
	s_and_saveexec_b64 s[14:15], s[40:41]
	s_cbranch_execz .LBB0_298
	v_add_u32_e32 v50, v158, v157
	ds_write_b128 v50, v[38:41] offset:32
	ds_write_b128 v50, v[34:37] offset:48
.LBB0_298:
	s_or_b64 exec, exec, s[14:15]
	v_mov_b32_e32 v105, v104
	v_pk_mul_f32 v[38:39], v[104:105], v[38:39]
	v_pk_mul_f32 v[40:41], v[104:105], v[40:41]
	v_pk_mul_f32 v[34:35], v[104:105], v[34:35]
	v_cvt_pk_bf16_f32 v38, v38, v39
	v_cvt_pk_bf16_f32 v39, v40, v41
	v_cvt_pk_bf16_f32 v40, v34, v35
	v_pk_mul_f32 v[34:35], v[104:105], v[36:37]
	v_pk_mul_f32 v[42:43], v[68:69], v[42:43]
	v_cvt_pk_bf16_f32 v41, v34, v35
	ds_write_b128 v202, v[38:41] offset:16
	global_load_dwordx4 v[34:37], v[70:71], off offset:64
	global_load_dwordx4 v[50:53], v[70:71], off offset:80
	v_pk_mul_f32 v[38:39], v[68:69], v[58:59]
	v_pk_mul_f32 v[40:41], v[68:69], v[60:61]
	v_pk_mul_f32 v[44:45], v[68:69], v[44:45]
	s_waitcnt vmcnt(1)
	v_pk_mul_f32 v[38:39], v[38:39], v[34:35]
	v_pk_mul_f32 v[40:41], v[40:41], v[36:37]
	s_waitcnt vmcnt(0)
	v_pk_mul_f32 v[34:35], v[42:43], v[50:51]
	v_pk_mul_f32 v[36:37], v[44:45], v[52:53]
	s_and_saveexec_b64 s[14:15], s[40:41]
	s_cbranch_execz .LBB0_300
	v_add_u32_e32 v42, v158, v157
	ds_write_b128 v42, v[38:41] offset:64
	ds_write_b128 v42, v[34:37] offset:80
.LBB0_300:
	s_or_b64 exec, exec, s[14:15]
	v_pk_mul_f32 v[38:39], v[104:105], v[38:39]
	v_pk_mul_f32 v[40:41], v[104:105], v[40:41]
	v_pk_mul_f32 v[34:35], v[104:105], v[34:35]
	v_cvt_pk_bf16_f32 v38, v38, v39
	v_cvt_pk_bf16_f32 v39, v40, v41
	v_cvt_pk_bf16_f32 v40, v34, v35
	v_pk_mul_f32 v[34:35], v[104:105], v[36:37]
	v_pk_mul_f32 v[46:47], v[68:69], v[46:47]
	v_cvt_pk_bf16_f32 v41, v34, v35
	ds_write_b128 v202, v[38:41] offset:32
	global_load_dwordx4 v[34:37], v[70:71], off offset:96
	global_load_dwordx4 v[42:45], v[70:71], off offset:112
	v_pk_mul_f32 v[38:39], v[68:69], v[62:63]
	v_pk_mul_f32 v[40:41], v[68:69], v[64:65]
	v_pk_mul_f32 v[48:49], v[68:69], v[48:49]
	s_waitcnt vmcnt(1)
	v_pk_mul_f32 v[38:39], v[38:39], v[34:35]
	v_pk_mul_f32 v[40:41], v[40:41], v[36:37]
	s_waitcnt vmcnt(0)
	v_pk_mul_f32 v[34:35], v[46:47], v[42:43]
	v_pk_mul_f32 v[36:37], v[48:49], v[44:45]
	s_and_saveexec_b64 s[14:15], s[40:41]
	s_cbranch_execz .LBB0_302
	v_add_u32_e32 v42, v158, v157
	ds_write_b128 v42, v[38:41] offset:96
	ds_write_b128 v42, v[34:37] offset:112
.LBB0_302:
	s_or_b64 exec, exec, s[14:15]
	v_pk_mul_f32 v[38:39], v[104:105], v[38:39]
	v_pk_mul_f32 v[40:41], v[104:105], v[40:41]
	v_pk_mul_f32 v[34:35], v[104:105], v[34:35]
	v_cvt_pk_bf16_f32 v38, v38, v39
	v_cvt_pk_bf16_f32 v39, v40, v41
	v_cvt_pk_bf16_f32 v40, v34, v35
	v_pk_mul_f32 v[34:35], v[104:105], v[36:37]
	s_and_b64 s[12:13], s[4:5], s[12:13]
	v_cvt_pk_bf16_f32 v41, v34, v35
	ds_write_b128 v202, v[38:41] offset:48
	ds_read_b128 v[176:179], v204
	ds_read_b128 v[180:183], v204 offset:144
	ds_read_b128 v[184:187], v204 offset:288
	ds_read_b128 v[188:191], v204 offset:432
	s_cmp_lg_u64 s[98:99], 0
	s_cbranch_scc0 .Lg1co_k3
	v_lshl_add_u64 v[192:193], v[72:73], 0, v[206:207]
	s_waitcnt lgkmcnt(3)
	global_store_dwordx4 v[192:193], v[176:179], off
	s_waitcnt lgkmcnt(2)
	global_store_dwordx4 v[192:193], v[180:183], off offset:1024
	s_waitcnt lgkmcnt(1)
	global_store_dwordx4 v[192:193], v[184:187], off offset:2048
	s_waitcnt lgkmcnt(0)
	global_store_dwordx4 v[192:193], v[188:191], off offset:3072
	s_branch .Lg1co_e3
.Lg1co_k3:
	v_lshl_add_u64 v[192:193], v[72:73], 0, v[208:209]
	s_waitcnt lgkmcnt(3)
	global_store_dwordx4 v[192:193], v[176:179], off
	s_waitcnt lgkmcnt(2)
	global_store_dwordx4 v[192:193], v[180:183], off offset:128
	s_waitcnt lgkmcnt(1)
	global_store_dwordx4 v[192:193], v[184:187], off offset:256
	s_waitcnt lgkmcnt(0)
	global_store_dwordx4 v[192:193], v[188:191], off offset:384
.Lg1co_e3:
	s_and_saveexec_b64 s[14:15], s[12:13]
	s_cbranch_execz .LBB0_319
	v_ashrrev_i32_e32 v67, 31, v66
	v_lshlrev_b64 v[34:35], 11, v[66:67]
	v_lshl_add_u64 v[34:35], s[28:29], 0, v[34:35]
	v_lshl_add_u64 v[34:35], v[102:103], 2, v[34:35]
	v_lshlrev_b32_e32 v36, 2, v155
	v_mov_b32_e32 v37, v99
	v_lshl_add_u64 v[34:35], v[34:35], 0, v[36:37]
	v_or_b32_e32 v36, v66, v154
	v_cmp_gt_i32_e64 s[12:13], s57, v36
	s_and_saveexec_b64 s[40:41], s[12:13]
	s_cbranch_execz .LBB0_305
	v_add_u32_e32 v36, v139, v152
	ds_read_b128 v[36:39], v36
	v_lshlrev_b32_e32 v40, 2, v153
	v_mov_b32_e32 v41, v99
	v_lshl_add_u64 v[40:41], v[34:35], 0, v[40:41]
	s_waitcnt lgkmcnt(0)
	global_store_dwordx4 v[40:41], v[36:39], off

.LBB0_321:
	s_andn2_saveexec_b64 s[12:13], s[36:37]
	s_cbranch_execz .LBB0_323
	v_ashrrev_i32_e32 v69, 31, v68
	v_lshlrev_b64 v[66:67], 10, v[68:69]
	v_mul_f32_e32 v68, 0xbfb8aa3b, v50
	v_exp_f32_e32 v70, v68
	v_lshl_add_u64 v[66:67], v[114:115], 0, v[66:67]
	v_cndmask_b32_e32 v68, v133, v134, vcc
	v_mov_b32_e32 v69, v99
	v_lshl_add_u64 v[66:67], v[66:67], 0, v[68:69]
	v_add_f32_e32 v68, 1.0, v70
	v_mul_f32_e32 v69, 0xbfb8aa3b, v34
	v_mul_f32_e32 v70, 0xbfb8aa3b, v51
	v_exp_f32_e32 v69, v69
	v_exp_f32_e32 v70, v70
	v_rcp_f32_e32 v68, v68
	v_mul_f32_e32 v71, 0xbfb8aa3b, v35
	v_add_f32_e32 v69, 1.0, v69
	v_add_f32_e32 v70, 1.0, v70
	v_rcp_f32_e32 v69, v69
	v_rcp_f32_e32 v70, v70
	v_mul_f32_e32 v50, v50, v68
	v_exp_f32_e32 v71, v71
	v_mul_f32_e32 v68, v34, v69
	v_mul_f32_e32 v51, v51, v70
	v_mul_f32_e32 v69, 0xbfb8aa3b, v52
	v_mul_f32_e32 v70, 0xbfb8aa3b, v36
	v_exp_f32_e32 v69, v69
	v_exp_f32_e32 v70, v70
	v_add_f32_e32 v34, 1.0, v71
	v_rcp_f32_e32 v34, v34
	v_add_f32_e32 v69, 1.0, v69
	v_add_f32_e32 v70, 1.0, v70
	v_rcp_f32_e32 v69, v69
	v_rcp_f32_e32 v70, v70
	v_mul_f32_e32 v72, v35, v34
	v_mul_f32_e32 v35, 0xbfb8aa3b, v37
	v_mul_f32_e32 v52, v52, v69
	v_mul_f32_e32 v69, v36, v70
	v_mul_f32_e32 v36, 0xbfb8aa3b, v54
	v_exp_f32_e32 v35, v35
	v_exp_f32_e32 v36, v36
	v_mul_f32_e32 v71, 0xbfb8aa3b, v53
	v_exp_f32_e32 v71, v71
	v_add_f32_e32 v35, 1.0, v35
	v_add_f32_e32 v36, 1.0, v36
	v_rcp_f32_e32 v35, v35
	v_rcp_f32_e32 v36, v36
	v_add_f32_e32 v34, 1.0, v71
	v_mul_f32_e32 v70, 0xbfb8aa3b, v38
	v_mul_f32_e32 v37, v37, v35
	v_mul_f32_e32 v54, v54, v36
	v_mul_f32_e32 v35, 0xbfb8aa3b, v55
	v_mul_f32_e32 v36, 0xbfb8aa3b, v39
	v_exp_f32_e32 v35, v35
	v_exp_f32_e32 v36, v36
	v_rcp_f32_e32 v34, v34
	v_exp_f32_e32 v70, v70
	v_add_f32_e32 v35, 1.0, v35
	v_add_f32_e32 v36, 1.0, v36
	v_rcp_f32_e32 v35, v35
	v_rcp_f32_e32 v36, v36
	v_mul_f32_e32 v53, v53, v34
	v_add_f32_e32 v34, 1.0, v70
	v_mul_f32_e32 v55, v55, v35
	v_mul_f32_e32 v73, v39, v36
	v_mul_f32_e32 v35, 0xbfb8aa3b, v40
	v_mul_f32_e32 v36, 0xbfb8aa3b, v57
	v_exp_f32_e32 v35, v35
	v_exp_f32_e32 v36, v36
	v_mul_f32_e32 v70, 0xbfb8aa3b, v56
	v_rcp_f32_e32 v34, v34
	v_add_f32_e32 v35, 1.0, v35
	v_add_f32_e32 v36, 1.0, v36
	v_rcp_f32_e32 v35, v35
	v_rcp_f32_e32 v36, v36
	v_exp_f32_e32 v70, v70
	v_mul_f32_e32 v71, v38, v34
	v_mul_f32_e32 v40, v40, v35
	v_mul_f32_e32 v57, v57, v36
	v_mul_f32_e32 v35, 0xbfb8aa3b, v58
	v_mul_f32_e32 v36, 0xbfb8aa3b, v42
	v_exp_f32_e32 v35, v35
	v_exp_f32_e32 v36, v36
	v_add_f32_e32 v34, 1.0, v70
	v_mul_f32_e32 v38, 0xbfb8aa3b, v41
	v_add_f32_e32 v35, 1.0, v35
	v_add_f32_e32 v36, 1.0, v36
	v_rcp_f32_e32 v35, v35
	v_rcp_f32_e32 v36, v36
	v_rcp_f32_e32 v34, v34
	v_exp_f32_e32 v38, v38
	v_mul_f32_e32 v58, v58, v35
	v_mul_f32_e32 v42, v42, v36
	v_mul_f32_e32 v35, 0xbfb8aa3b, v43
	v_mul_f32_e32 v36, 0xbfb8aa3b, v60
	v_exp_f32_e32 v35, v35
	v_exp_f32_e32 v36, v36
	v_mul_f32_e32 v56, v56, v34
	v_add_f32_e32 v34, 1.0, v38
	v_add_f32_e32 v35, 1.0, v35
	v_add_f32_e32 v36, 1.0, v36
	v_rcp_f32_e32 v35, v35
	v_rcp_f32_e32 v36, v36
	v_mul_f32_e32 v38, 0xbfb8aa3b, v59
	v_rcp_f32_e32 v34, v34
	v_mul_f32_e32 v43, v43, v35
	v_mul_f32_e32 v60, v60, v36
	v_mul_f32_e32 v35, 0xbfb8aa3b, v61
	v_mul_f32_e32 v36, 0xbfb8aa3b, v45
	v_exp_f32_e32 v38, v38
	v_exp_f32_e32 v35, v35
	v_exp_f32_e32 v36, v36
	v_mul_f32_e32 v41, v41, v34
	v_add_f32_e32 v34, 1.0, v38
	v_mul_f32_e32 v38, 0xbfb8aa3b, v44
	v_add_f32_e32 v35, 1.0, v35
	v_add_f32_e32 v36, 1.0, v36
	v_rcp_f32_e32 v34, v34
	v_exp_f32_e32 v38, v38
	v_rcp_f32_e32 v35, v35
	v_rcp_f32_e32 v36, v36
	v_mul_f32_e32 v59, v59, v34
	v_add_f32_e32 v34, 1.0, v38
	v_mul_f32_e32 v38, 0xbfb8aa3b, v62
	v_mul_f32_e32 v61, v61, v35
	v_mul_f32_e32 v45, v45, v36
	v_mul_f32_e32 v35, 0xbfb8aa3b, v46
	v_mul_f32_e32 v36, 0xbfb8aa3b, v63
	v_rcp_f32_e32 v34, v34
	v_exp_f32_e32 v38, v38
	v_exp_f32_e32 v35, v35
	v_exp_f32_e32 v36, v36
	v_mul_f32_e32 v44, v44, v34
	v_add_f32_e32 v34, 1.0, v38
	v_add_f32_e32 v35, 1.0, v35
	v_add_f32_e32 v36, 1.0, v36
	v_mul_f32_e32 v38, 0xbfb8aa3b, v47
	v_rcp_f32_e32 v34, v34
	v_rcp_f32_e32 v35, v35
	v_rcp_f32_e32 v36, v36
	v_exp_f32_e32 v38, v38
	v_mul_f32_e32 v62, v62, v34
	v_mul_f32_e32 v46, v46, v35
	v_mul_f32_e32 v63, v63, v36
	v_add_f32_e32 v34, 1.0, v38
	v_mul_f32_e32 v35, 0xbfb8aa3b, v64
	v_mul_f32_e32 v36, 0xbfb8aa3b, v48
	v_rcp_f32_e32 v34, v34
	v_exp_f32_e32 v35, v35
	v_exp_f32_e32 v36, v36
	v_mul_f32_e32 v38, 0xbfb8aa3b, v49
	v_mul_f32_e32 v47, v47, v34
	v_add_f32_e32 v34, 1.0, v35
	v_add_f32_e32 v35, 1.0, v36
	v_mul_f32_e32 v36, 0xbfb8aa3b, v65
	v_exp_f32_e32 v36, v36
	v_exp_f32_e32 v38, v38
	v_rcp_f32_e32 v34, v34
	v_rcp_f32_e32 v35, v35
	v_add_f32_e32 v36, 1.0, v36
	v_add_f32_e32 v38, 1.0, v38
	v_rcp_f32_e32 v36, v36
	v_rcp_f32_e32 v38, v38
	v_mul_f32_e32 v64, v64, v34
	v_mul_f32_e32 v48, v48, v35
	v_permlane32_swap_b32_e32 v50, v68
	v_permlane32_swap_b32_e32 v51, v72
	v_permlane32_swap_b32_e32 v52, v69
	v_permlane32_swap_b32_e32 v53, v37
	v_lshlrev_b32_e32 v34, 1, v100
	v_mov_b32_e32 v35, v99
	v_mul_f32_e32 v65, v65, v36
	v_mul_f32_e32 v49, v49, v38
	v_permlane32_swap_b32_e32 v54, v71
	v_permlane32_swap_b32_e32 v55, v73
	v_permlane32_swap_b32_e32 v56, v40
	v_permlane32_swap_b32_e32 v57, v41
	v_lshl_add_u64 v[38:39], v[66:67], 0, v[34:35]
	v_cvt_pk_bf16_f32 v34, v50, v51
	v_cvt_pk_bf16_f32 v35, v52, v53
	v_cvt_pk_bf16_f32 v36, v68, v72
	v_cvt_pk_bf16_f32 v37, v69, v37
	v_permlane32_swap_b32_e32 v58, v42
	v_permlane32_swap_b32_e32 v59, v43
	v_permlane32_swap_b32_e32 v60, v44
	v_permlane32_swap_b32_e32 v61, v45
	ds_write_b128 v202, v[34:37]
	v_permlane32_swap_b32_e32 v62, v46
	s_nop 0
	v_cvt_pk_bf16_f32 v34, v54, v55
	v_cvt_pk_bf16_f32 v35, v56, v57
	v_cvt_pk_bf16_f32 v36, v71, v73
	v_cvt_pk_bf16_f32 v37, v40, v41
	v_permlane32_swap_b32_e32 v63, v47
	v_permlane32_swap_b32_e32 v64, v48
	v_permlane32_swap_b32_e32 v65, v49
	ds_write_b128 v202, v[34:37] offset:16
	s_nop 1
	v_cvt_pk_bf16_f32 v34, v58, v59
	v_cvt_pk_bf16_f32 v35, v60, v61
	v_cvt_pk_bf16_f32 v36, v42, v43
	v_cvt_pk_bf16_f32 v37, v44, v45
	ds_write_b128 v202, v[34:37] offset:32
	s_nop 1
	v_cvt_pk_bf16_f32 v34, v62, v63
	v_cvt_pk_bf16_f32 v35, v64, v65
	v_cvt_pk_bf16_f32 v36, v46, v47
	v_cvt_pk_bf16_f32 v37, v48, v49
	ds_write_b128 v202, v[34:37] offset:48
	v_lshl_add_u64 v[192:193], v[38:39], 0, v[206:207]
	ds_read_b128 v[176:179], v204
	ds_read_b128 v[180:183], v204 offset:144
	ds_read_b128 v[184:187], v204 offset:288
	ds_read_b128 v[188:191], v204 offset:432
	s_waitcnt lgkmcnt(3)
	global_store_dwordx4 v[192:193], v[176:179], off
	s_waitcnt lgkmcnt(2)
	global_store_dwordx4 v[192:193], v[180:183], off offset:1024
	s_waitcnt lgkmcnt(1)
	global_store_dwordx4 v[192:193], v[184:187], off offset:2048
	s_waitcnt lgkmcnt(0)
	global_store_dwordx4 v[192:193], v[188:191], off offset:3072

.LBB0_324:
	s_andn2_saveexec_b64 s[14:15], s[34:35]
	s_cbranch_execz .LBB0_326
	v_mul_f32_e32 v34, 0xbfb8aa3b, v34
	v_mul_f32_e32 v35, 0xbfb8aa3b, v35
	v_exp_f32_e32 v34, v34
	v_exp_f32_e32 v35, v35
	v_mul_f32_e32 v36, 0xbfb8aa3b, v36
	v_exp_f32_e32 v36, v36
	v_add_f32_e32 v34, 1.0, v34
	v_add_f32_e32 v35, 1.0, v35
	v_rcp_f32_e32 v34, v34
	v_rcp_f32_e32 v35, v35
	v_cmp_gt_i32_e64 s[12:13], s57, v68
	v_mul_f32_e32 v50, v50, v34
	v_mul_f32_e32 v51, v51, v35
	v_add_f32_e32 v34, 1.0, v36
	v_mul_f32_e32 v35, 0xbfb8aa3b, v37
	v_mul_f32_e32 v36, 0xbfb8aa3b, v38
	v_exp_f32_e32 v35, v35
	v_exp_f32_e32 v36, v36
	v_mul_f32_e32 v37, 0xbfb8aa3b, v39
	v_rcp_f32_e32 v34, v34
	v_add_f32_e32 v35, 1.0, v35
	v_add_f32_e32 v36, 1.0, v36
	v_rcp_f32_e32 v35, v35
	v_rcp_f32_e32 v36, v36
	v_exp_f32_e32 v37, v37
	v_mul_f32_e32 v52, v52, v34
	v_mul_f32_e32 v53, v53, v35
	v_mul_f32_e32 v54, v54, v36
	v_mul_f32_e32 v35, 0xbfb8aa3b, v40
	v_mul_f32_e32 v36, 0xbfb8aa3b, v41
	v_exp_f32_e32 v35, v35
	v_exp_f32_e32 v36, v36
	v_add_f32_e32 v34, 1.0, v37
	v_mul_f32_e32 v37, 0xbfb8aa3b, v42
	v_add_f32_e32 v35, 1.0, v35
	v_add_f32_e32 v36, 1.0, v36
	v_rcp_f32_e32 v35, v35
	v_rcp_f32_e32 v36, v36
	v_rcp_f32_e32 v34, v34
	v_exp_f32_e32 v37, v37
	v_mul_f32_e32 v41, v56, v35
	v_mul_f32_e32 v42, v57, v36
	v_mul_f32_e32 v35, 0xbfb8aa3b, v43
	v_mul_f32_e32 v36, 0xbfb8aa3b, v44
	v_exp_f32_e32 v35, v35
	v_exp_f32_e32 v36, v36
	v_mul_f32_e32 v40, v55, v34
	v_add_f32_e32 v34, 1.0, v37
	v_add_f32_e32 v35, 1.0, v35
	v_add_f32_e32 v36, 1.0, v36
	v_mul_f32_e32 v37, 0xbfb8aa3b, v45
	v_rcp_f32_e32 v34, v34
	v_rcp_f32_e32 v35, v35
	v_rcp_f32_e32 v36, v36
	v_exp_f32_e32 v37, v37
	v_mul_f32_e32 v43, v58, v34
	v_mul_f32_e32 v44, v59, v35
	v_mul_f32_e32 v45, v60, v36
	v_add_f32_e32 v34, 1.0, v37
	v_mul_f32_e32 v35, 0xbfb8aa3b, v46
	v_mul_f32_e32 v36, 0xbfb8aa3b, v47
	v_rcp_f32_e32 v34, v34
	v_exp_f32_e32 v35, v35
	v_exp_f32_e32 v36, v36
	v_mul_f32_e32 v38, 0xbfb8aa3b, v49
	v_mul_f32_e32 v37, v61, v34
	v_add_f32_e32 v34, 1.0, v35
	v_add_f32_e32 v35, 1.0, v36
	v_rcp_f32_e32 v35, v35
	v_mul_f32_e32 v36, 0xbfb8aa3b, v48
	v_rcp_f32_e32 v34, v34
	v_exp_f32_e32 v36, v36
	v_exp_f32_e32 v38, v38
	v_mul_f32_e32 v47, v63, v35
	v_add_u32_e32 v35, 0xffffe020, v108
	v_lshrrev_b32_e32 v35, 12, v35
	v_add_f32_e32 v36, 1.0, v36
	v_add_f32_e32 v38, 1.0, v38
	v_mul_f32_e32 v46, v62, v34
	v_ashrrev_i32_e32 v34, 8, v66
	v_add_u32_e32 v35, 32, v35
	v_rcp_f32_e32 v36, v36
	v_rcp_f32_e32 v38, v38
	v_cndmask_b32_e64 v34, v35, v34, s[12:13]
	v_lshlrev_b32_e32 v34, 5, v34
	v_add3_u32 v34, v68, v34, 16
	v_ashrrev_i32_e32 v35, 31, v34
	v_mul_f32_e32 v48, v64, v36
	v_mul_f32_e32 v49, v65, v38
	v_permlane32_swap_b32_e32 v50, v43
	v_permlane32_swap_b32_e32 v51, v44
	v_permlane32_swap_b32_e32 v52, v45
	v_permlane32_swap_b32_e32 v53, v37
	v_lshlrev_b64 v[34:35], 10, v[34:35]
	v_permlane32_swap_b32_e32 v54, v46
	v_permlane32_swap_b32_e32 v40, v47
	v_permlane32_swap_b32_e32 v41, v48
	v_permlane32_swap_b32_e32 v42, v49
	v_lshl_add_u64 v[38:39], v[116:117], 0, v[34:35]
	v_cvt_pk_bf16_f32 v34, v50, v51
	v_cvt_pk_bf16_f32 v35, v52, v53
	v_cvt_pk_bf16_f32 v36, v43, v44
	v_cvt_pk_bf16_f32 v37, v45, v37
	ds_write_b128 v203, v[34:37]
	s_nop 1
	v_cvt_pk_bf16_f32 v34, v54, v40
	v_cvt_pk_bf16_f32 v35, v41, v42
	v_cvt_pk_bf16_f32 v36, v46, v47
	v_cvt_pk_bf16_f32 v37, v48, v49
	ds_write_b128 v203, v[34:37] offset:16
	v_lshl_add_u64 v[192:193], v[38:39], 0, v[210:211]
	ds_read_b128 v[176:179], v205
	ds_read_b128 v[180:183], v205 offset:144
	s_waitcnt lgkmcnt(1)
	global_store_dwordx4 v[192:193], v[176:179], off
	s_waitcnt lgkmcnt(0)
	global_store_dwordx4 v[192:193], v[180:183], off offset:1024

.LBB0_355:
	s_or_b64 exec, exec, s[6:7]
	v_pk_mul_f32 v[18:19], v[104:105], v[18:19] op_sel_hi:[0,1]
	v_pk_mul_f32 v[20:21], v[104:105], v[20:21] op_sel_hi:[0,1]
	v_pk_mul_f32 v[2:3], v[104:105], v[2:3] op_sel_hi:[0,1]
	v_lshlrev_b32_e32 v98, 1, v100
	v_cvt_pk_bf16_f32 v18, v18, v19
	v_cvt_pk_bf16_f32 v19, v20, v21
	v_cvt_pk_bf16_f32 v20, v2, v3
	v_pk_mul_f32 v[2:3], v[104:105], v[4:5] op_sel_hi:[0,1]
	v_lshl_add_u64 v[40:41], v[40:41], 0, v[98:99]
	v_cvt_pk_bf16_f32 v21, v2, v3
	ds_write_b128 v202, v[18:21]
	global_load_dwordx4 v[2:5], v[38:39], off offset:32
	s_nop 0
	global_load_dwordx4 v[18:21], v[38:39], off offset:48
	v_mov_b32_e32 v37, v36
	v_pk_mul_f32 v[6:7], v[36:37], v[6:7]
	v_pk_mul_f32 v[8:9], v[36:37], v[8:9]
	v_pk_mul_f32 v[22:23], v[36:37], v[22:23]
	v_pk_mul_f32 v[24:25], v[36:37], v[24:25]
	s_waitcnt vmcnt(1)
	v_pk_mul_f32 v[6:7], v[6:7], v[2:3]
	v_pk_mul_f32 v[8:9], v[8:9], v[4:5]
	s_waitcnt vmcnt(0)
	v_pk_mul_f32 v[2:3], v[22:23], v[18:19]
	v_pk_mul_f32 v[4:5], v[24:25], v[20:21]
	s_and_saveexec_b64 s[6:7], s[10:11]
	s_cbranch_execz .LBB0_357
	ds_write_b128 v35, v[6:9] offset:32
	ds_write_b128 v35, v[2:5] offset:48
.LBB0_357:
	s_or_b64 exec, exec, s[6:7]
	v_mov_b32_e32 v105, v104
	v_pk_mul_f32 v[6:7], v[104:105], v[6:7]
	v_pk_mul_f32 v[8:9], v[104:105], v[8:9]
	v_pk_mul_f32 v[2:3], v[104:105], v[2:3]
	v_cvt_pk_bf16_f32 v6, v6, v7
	v_cvt_pk_bf16_f32 v7, v8, v9
	v_cvt_pk_bf16_f32 v8, v2, v3
	v_pk_mul_f32 v[2:3], v[104:105], v[4:5]
	s_nop 0
	v_cvt_pk_bf16_f32 v9, v2, v3
	ds_write_b128 v202, v[6:9] offset:16
	global_load_dwordx4 v[2:5], v[38:39], off offset:64
	global_load_dwordx4 v[18:21], v[38:39], off offset:80
	v_pk_mul_f32 v[6:7], v[36:37], v[10:11]
	v_pk_mul_f32 v[8:9], v[36:37], v[12:13]
	v_pk_mul_f32 v[10:11], v[36:37], v[26:27]
	v_pk_mul_f32 v[12:13], v[36:37], v[28:29]
	s_waitcnt vmcnt(1)
	v_pk_mul_f32 v[6:7], v[6:7], v[2:3]
	v_pk_mul_f32 v[8:9], v[8:9], v[4:5]
	s_waitcnt vmcnt(0)
	v_pk_mul_f32 v[2:3], v[10:11], v[18:19]
	v_pk_mul_f32 v[4:5], v[12:13], v[20:21]
	s_and_saveexec_b64 s[6:7], s[10:11]
	s_cbranch_execz .LBB0_359
	ds_write_b128 v35, v[6:9] offset:64
	ds_write_b128 v35, v[2:5] offset:80
.LBB0_359:
	s_or_b64 exec, exec, s[6:7]
	v_pk_mul_f32 v[6:7], v[104:105], v[6:7]
	v_pk_mul_f32 v[8:9], v[104:105], v[8:9]
	v_pk_mul_f32 v[2:3], v[104:105], v[2:3]
	v_cvt_pk_bf16_f32 v6, v6, v7
	v_cvt_pk_bf16_f32 v7, v8, v9
	v_cvt_pk_bf16_f32 v8, v2, v3
	v_pk_mul_f32 v[2:3], v[104:105], v[4:5]
	s_nop 0
	v_cvt_pk_bf16_f32 v9, v2, v3
	ds_write_b128 v202, v[6:9] offset:32
	global_load_dwordx4 v[2:5], v[38:39], off offset:96
	global_load_dwordx4 v[10:13], v[38:39], off offset:112
	v_pk_mul_f32 v[6:7], v[36:37], v[14:15]
	v_pk_mul_f32 v[8:9], v[36:37], v[16:17]
	v_pk_mul_f32 v[14:15], v[36:37], v[30:31]
	v_pk_mul_f32 v[16:17], v[36:37], v[32:33]
	s_waitcnt vmcnt(1)
	v_pk_mul_f32 v[6:7], v[6:7], v[2:3]
	v_pk_mul_f32 v[8:9], v[8:9], v[4:5]
	s_waitcnt vmcnt(0)
	v_pk_mul_f32 v[2:3], v[14:15], v[10:11]
	v_pk_mul_f32 v[4:5], v[16:17], v[12:13]
	s_and_saveexec_b64 s[6:7], s[10:11]
	s_cbranch_execz .LBB0_361
	ds_write_b128 v35, v[6:9] offset:96
	ds_write_b128 v35, v[2:5] offset:112
.LBB0_361:
	s_or_b64 exec, exec, s[6:7]
	v_pk_mul_f32 v[6:7], v[104:105], v[6:7]
	v_pk_mul_f32 v[8:9], v[104:105], v[8:9]
	v_pk_mul_f32 v[2:3], v[104:105], v[2:3]
	v_cvt_pk_bf16_f32 v6, v6, v7
	v_cvt_pk_bf16_f32 v7, v8, v9
	v_cvt_pk_bf16_f32 v8, v2, v3
	v_pk_mul_f32 v[2:3], v[104:105], v[4:5]
	s_and_b64 s[4:5], s[4:5], s[8:9]
	v_cvt_pk_bf16_f32 v9, v2, v3
	ds_write_b128 v202, v[6:9] offset:48
	ds_read_b128 v[176:179], v204
	ds_read_b128 v[180:183], v204 offset:144
	ds_read_b128 v[184:187], v204 offset:288
	ds_read_b128 v[188:191], v204 offset:432
	s_cmp_lg_u64 s[98:99], 0
	s_cbranch_scc0 .Lg1co_k6
	v_lshl_add_u64 v[192:193], v[40:41], 0, v[206:207]
	s_waitcnt lgkmcnt(3)
	global_store_dwordx4 v[192:193], v[176:179], off
	s_waitcnt lgkmcnt(2)
	global_store_dwordx4 v[192:193], v[180:183], off offset:1024
	s_waitcnt lgkmcnt(1)
	global_store_dwordx4 v[192:193], v[184:187], off offset:2048
	s_waitcnt lgkmcnt(0)
	global_store_dwordx4 v[192:193], v[188:191], off offset:3072
	s_branch .Lg1co_e6
.Lg1co_k6:
	v_lshl_add_u64 v[192:193], v[40:41], 0, v[208:209]
	s_waitcnt lgkmcnt(3)
	global_store_dwordx4 v[192:193], v[176:179], off
	s_waitcnt lgkmcnt(2)
	global_store_dwordx4 v[192:193], v[180:183], off offset:128
	s_waitcnt lgkmcnt(1)
	global_store_dwordx4 v[192:193], v[184:187], off offset:256
	s_waitcnt lgkmcnt(0)
	global_store_dwordx4 v[192:193], v[188:191], off offset:384
.Lg1co_e6:
	s_and_saveexec_b64 s[6:7], s[4:5]
	s_cbranch_execz .LBB0_378
	v_ashrrev_i32_e32 v35, 31, v34
	v_lshlrev_b64 v[2:3], 11, v[34:35]
	v_lshl_add_u64 v[2:3], s[28:29], 0, v[2:3]
	v_lshl_add_u64 v[2:3], v[102:103], 2, v[2:3]
	v_lshlrev_b32_e32 v98, 2, v155
	v_or_b32_e32 v4, v34, v154
	v_lshl_add_u64 v[2:3], v[2:3], 0, v[98:99]
	v_cmp_gt_i32_e64 s[4:5], s57, v4
	s_and_saveexec_b64 s[8:9], s[4:5]
	s_cbranch_execz .LBB0_364
	v_add_u32_e32 v4, v139, v152
	ds_read_b128 v[4:7], v4
	v_lshlrev_b32_e32 v98, 2, v153
	v_lshl_add_u64 v[8:9], v[2:3], 0, v[98:99]
	s_waitcnt lgkmcnt(0)
	global_store_dwordx4 v[8:9], v[4:7], off

.LBB0_380:
	s_andn2_saveexec_b64 s[4:5], s[14:15]
	s_cbranch_execz .LBB0_382
	v_ashrrev_i32_e32 v37, 31, v36
	v_lshlrev_b64 v[34:35], 10, v[36:37]
	v_mul_f32_e32 v37, 0xbfb8aa3b, v18
	v_mul_f32_e32 v38, 0xbfb8aa3b, v3
	v_exp_f32_e32 v37, v37
	v_exp_f32_e32 v38, v38
	v_mul_f32_e32 v36, 0xbfb8aa3b, v2
	v_exp_f32_e32 v36, v36
	v_add_f32_e32 v37, 1.0, v37
	v_add_f32_e32 v38, 1.0, v38
	v_rcp_f32_e32 v37, v37
	v_rcp_f32_e32 v38, v38
	v_add_f32_e32 v36, 1.0, v36
	v_mul_f32_e32 v39, 0xbfb8aa3b, v19
	v_mul_f32_e32 v18, v18, v37
	v_mul_f32_e32 v3, v3, v38
	v_mul_f32_e32 v37, 0xbfb8aa3b, v4
	v_mul_f32_e32 v38, 0xbfb8aa3b, v20
	v_exp_f32_e32 v37, v37
	v_exp_f32_e32 v38, v38
	v_rcp_f32_e32 v36, v36
	v_exp_f32_e32 v39, v39
	v_add_f32_e32 v37, 1.0, v37
	v_add_f32_e32 v38, 1.0, v38
	v_rcp_f32_e32 v37, v37
	v_rcp_f32_e32 v38, v38
	v_mul_f32_e32 v2, v2, v36
	v_add_f32_e32 v36, 1.0, v39
	v_mul_f32_e32 v39, 0xbfb8aa3b, v5
	v_mul_f32_e32 v4, v4, v37
	v_mul_f32_e32 v20, v20, v38
	v_mul_f32_e32 v37, 0xbfb8aa3b, v21
	v_mul_f32_e32 v38, 0xbfb8aa3b, v6
	v_rcp_f32_e32 v36, v36
	v_exp_f32_e32 v39, v39
	v_exp_f32_e32 v37, v37
	v_exp_f32_e32 v38, v38
	v_mul_f32_e32 v19, v19, v36
	v_add_f32_e32 v36, 1.0, v39
	v_add_f32_e32 v37, 1.0, v37
	v_add_f32_e32 v38, 1.0, v38
	v_rcp_f32_e32 v36, v36
	v_rcp_f32_e32 v37, v37
	v_rcp_f32_e32 v38, v38
	v_mul_f32_e32 v39, 0xbfb8aa3b, v22
	v_mul_f32_e32 v5, v5, v36
	v_mul_f32_e32 v21, v21, v37
	v_mul_f32_e32 v36, v6, v38
	v_mul_f32_e32 v37, 0xbfb8aa3b, v7
	v_mul_f32_e32 v38, 0xbfb8aa3b, v23
	v_exp_f32_e32 v37, v37
	v_exp_f32_e32 v38, v38
	v_exp_f32_e32 v39, v39
	v_lshl_add_u64 v[34:35], v[114:115], 0, v[34:35]
	v_add_f32_e32 v37, 1.0, v37
	v_add_f32_e32 v38, 1.0, v38
	v_rcp_f32_e32 v37, v37
	v_rcp_f32_e32 v38, v38
	v_add_f32_e32 v6, 1.0, v39
	v_mul_f32_e32 v39, 0xbfb8aa3b, v8
	v_mul_f32_e32 v37, v7, v37
	v_mul_f32_e32 v23, v23, v38
	v_mul_f32_e32 v7, 0xbfb8aa3b, v24
	v_mul_f32_e32 v38, 0xbfb8aa3b, v9
	v_exp_f32_e32 v7, v7
	v_exp_f32_e32 v38, v38
	v_rcp_f32_e32 v6, v6
	v_exp_f32_e32 v39, v39
	v_add_f32_e32 v7, 1.0, v7
	v_add_f32_e32 v38, 1.0, v38
	v_rcp_f32_e32 v7, v7
	v_rcp_f32_e32 v38, v38
	v_mul_f32_e32 v22, v22, v6
	v_add_f32_e32 v6, 1.0, v39
	v_mul_f32_e32 v24, v24, v7
	v_mul_f32_e32 v9, v9, v38
	v_mul_f32_e32 v7, 0xbfb8aa3b, v10
	v_mul_f32_e32 v38, 0xbfb8aa3b, v26
	v_exp_f32_e32 v7, v7
	v_exp_f32_e32 v38, v38
	v_mul_f32_e32 v39, 0xbfb8aa3b, v25
	v_rcp_f32_e32 v6, v6
	v_add_f32_e32 v7, 1.0, v7
	v_add_f32_e32 v38, 1.0, v38
	v_rcp_f32_e32 v7, v7
	v_rcp_f32_e32 v38, v38
	v_exp_f32_e32 v39, v39
	v_mul_f32_e32 v8, v8, v6
	v_mul_f32_e32 v10, v10, v7
	v_mul_f32_e32 v26, v26, v38
	v_mul_f32_e32 v7, 0xbfb8aa3b, v27
	v_mul_f32_e32 v38, 0xbfb8aa3b, v12
	v_exp_f32_e32 v7, v7
	v_exp_f32_e32 v38, v38
	v_add_f32_e32 v6, 1.0, v39
	v_mul_f32_e32 v39, 0xbfb8aa3b, v11
	v_add_f32_e32 v7, 1.0, v7
	v_add_f32_e32 v38, 1.0, v38
	v_rcp_f32_e32 v7, v7
	v_rcp_f32_e32 v38, v38
	v_rcp_f32_e32 v6, v6
	v_exp_f32_e32 v39, v39
	v_mul_f32_e32 v27, v27, v7
	v_mul_f32_e32 v12, v12, v38
	v_mul_f32_e32 v7, 0xbfb8aa3b, v13
	v_mul_f32_e32 v38, 0xbfb8aa3b, v29
	v_exp_f32_e32 v7, v7
	v_exp_f32_e32 v38, v38
	v_mul_f32_e32 v25, v25, v6
	v_add_f32_e32 v6, 1.0, v39
	v_mul_f32_e32 v39, 0xbfb8aa3b, v28
	v_add_f32_e32 v7, 1.0, v7
	v_add_f32_e32 v38, 1.0, v38
	v_rcp_f32_e32 v6, v6
	v_exp_f32_e32 v39, v39
	v_rcp_f32_e32 v7, v7
	v_rcp_f32_e32 v38, v38
	v_mul_f32_e32 v11, v11, v6
	v_add_f32_e32 v6, 1.0, v39
	v_mul_f32_e32 v39, 0xbfb8aa3b, v14
	v_mul_f32_e32 v13, v13, v7
	v_mul_f32_e32 v29, v29, v38
	v_mul_f32_e32 v7, 0xbfb8aa3b, v30
	v_mul_f32_e32 v38, 0xbfb8aa3b, v15
	v_rcp_f32_e32 v6, v6
	v_exp_f32_e32 v39, v39
	v_exp_f32_e32 v7, v7
	v_exp_f32_e32 v38, v38
	v_mul_f32_e32 v28, v28, v6
	v_add_f32_e32 v6, 1.0, v39
	v_add_f32_e32 v7, 1.0, v7
	v_add_f32_e32 v38, 1.0, v38
	v_mul_f32_e32 v39, 0xbfb8aa3b, v31
	v_rcp_f32_e32 v6, v6
	v_rcp_f32_e32 v7, v7
	v_rcp_f32_e32 v38, v38
	v_exp_f32_e32 v39, v39
	v_mul_f32_e32 v14, v14, v6
	v_mul_f32_e32 v30, v30, v7
	v_mul_f32_e32 v15, v15, v38
	v_add_f32_e32 v6, 1.0, v39
	v_mul_f32_e32 v7, 0xbfb8aa3b, v16
	v_mul_f32_e32 v38, 0xbfb8aa3b, v32
	v_rcp_f32_e32 v6, v6
	v_exp_f32_e32 v7, v7
	v_exp_f32_e32 v38, v38
	v_mul_f32_e32 v39, 0xbfb8aa3b, v33
	v_mul_f32_e32 v31, v31, v6
	v_add_f32_e32 v6, 1.0, v7
	v_add_f32_e32 v7, 1.0, v38
	v_mul_f32_e32 v38, 0xbfb8aa3b, v17
	v_exp_f32_e32 v38, v38
	v_exp_f32_e32 v39, v39
	v_rcp_f32_e32 v6, v6
	v_rcp_f32_e32 v7, v7
	v_add_f32_e32 v38, 1.0, v38
	v_add_f32_e32 v39, 1.0, v39
	v_rcp_f32_e32 v38, v38
	v_rcp_f32_e32 v39, v39
	v_cndmask_b32_e32 v98, v133, v134, vcc
	v_lshl_add_u64 v[34:35], v[34:35], 0, v[98:99]
	v_permlane32_swap_b32_e32 v2, v18
	v_permlane32_swap_b32_e32 v3, v19
	v_permlane32_swap_b32_e32 v4, v20
	v_permlane32_swap_b32_e32 v5, v21
	v_lshlrev_b32_e32 v98, 1, v100
	v_mul_f32_e32 v16, v16, v6
	v_mul_f32_e32 v32, v32, v7
	v_permlane32_swap_b32_e32 v36, v22
	v_permlane32_swap_b32_e32 v37, v23
	v_permlane32_swap_b32_e32 v8, v24
	v_permlane32_swap_b32_e32 v9, v25
	v_lshl_add_u64 v[6:7], v[34:35], 0, v[98:99]
	v_cvt_pk_bf16_f32 v2, v2, v3
	v_cvt_pk_bf16_f32 v3, v4, v5
	v_cvt_pk_bf16_f32 v4, v18, v19
	v_cvt_pk_bf16_f32 v5, v20, v21
	v_mul_f32_e32 v17, v17, v38
	v_mul_f32_e32 v33, v33, v39
	v_permlane32_swap_b32_e32 v10, v26
	v_permlane32_swap_b32_e32 v11, v27
	v_permlane32_swap_b32_e32 v12, v28
	v_permlane32_swap_b32_e32 v13, v29
	ds_write_b128 v202, v[2:5]
	v_permlane32_swap_b32_e32 v14, v30
	s_nop 0
	v_cvt_pk_bf16_f32 v2, v36, v37
	v_cvt_pk_bf16_f32 v3, v8, v9
	v_cvt_pk_bf16_f32 v4, v22, v23
	v_cvt_pk_bf16_f32 v5, v24, v25
	v_permlane32_swap_b32_e32 v15, v31
	v_permlane32_swap_b32_e32 v16, v32
	v_permlane32_swap_b32_e32 v17, v33
	ds_write_b128 v202, v[2:5] offset:16
	s_nop 1
	v_cvt_pk_bf16_f32 v2, v10, v11
	v_cvt_pk_bf16_f32 v3, v12, v13
	v_cvt_pk_bf16_f32 v4, v26, v27
	v_cvt_pk_bf16_f32 v5, v28, v29
	ds_write_b128 v202, v[2:5] offset:32
	s_nop 1
	v_cvt_pk_bf16_f32 v2, v14, v15
	v_cvt_pk_bf16_f32 v3, v16, v17
	v_cvt_pk_bf16_f32 v4, v30, v31
	v_cvt_pk_bf16_f32 v5, v32, v33
	ds_write_b128 v202, v[2:5] offset:48
	v_lshl_add_u64 v[192:193], v[6:7], 0, v[206:207]
	ds_read_b128 v[176:179], v204
	ds_read_b128 v[180:183], v204 offset:144
	ds_read_b128 v[184:187], v204 offset:288
	ds_read_b128 v[188:191], v204 offset:432
	s_waitcnt lgkmcnt(3)
	global_store_dwordx4 v[192:193], v[176:179], off
	s_waitcnt lgkmcnt(2)
	global_store_dwordx4 v[192:193], v[180:183], off offset:1024
	s_waitcnt lgkmcnt(1)
	global_store_dwordx4 v[192:193], v[184:187], off offset:2048
	s_waitcnt lgkmcnt(0)
	global_store_dwordx4 v[192:193], v[188:191], off offset:3072

.LBB0_383:
	v_mul_f32_e32 v18, 0xbfb8aa3b, v18
	v_mul_f32_e32 v19, 0xbfb8aa3b, v19
	v_exp_f32_e32 v18, v18
	v_exp_f32_e32 v19, v19
	v_mul_f32_e32 v20, 0xbfb8aa3b, v20
	v_exp_f32_e32 v20, v20
	v_add_f32_e32 v18, 1.0, v18
	v_add_f32_e32 v19, 1.0, v19
	v_rcp_f32_e32 v18, v18
	v_rcp_f32_e32 v19, v19
	v_cmp_gt_i32_e32 vcc, s57, v36
	v_mul_f32_e32 v18, v2, v18
	v_mul_f32_e32 v19, v3, v19
	v_add_f32_e32 v2, 1.0, v20
	v_mul_f32_e32 v3, 0xbfb8aa3b, v21
	v_mul_f32_e32 v20, 0xbfb8aa3b, v22
	v_exp_f32_e32 v3, v3
	v_exp_f32_e32 v20, v20
	v_mul_f32_e32 v21, 0xbfb8aa3b, v23
	v_rcp_f32_e32 v2, v2
	v_add_f32_e32 v3, 1.0, v3
	v_add_f32_e32 v20, 1.0, v20
	v_rcp_f32_e32 v3, v3
	v_rcp_f32_e32 v20, v20
	v_exp_f32_e32 v21, v21
	v_mul_f32_e32 v4, v4, v2
	v_mul_f32_e32 v5, v5, v3
	v_mul_f32_e32 v20, v6, v20
	v_mul_f32_e32 v3, 0xbfb8aa3b, v24
	v_mul_f32_e32 v6, 0xbfb8aa3b, v25
	v_exp_f32_e32 v3, v3
	v_exp_f32_e32 v6, v6
	v_add_f32_e32 v2, 1.0, v21
	v_mul_f32_e32 v21, 0xbfb8aa3b, v26
	v_add_f32_e32 v3, 1.0, v3
	v_add_f32_e32 v6, 1.0, v6
	v_rcp_f32_e32 v3, v3
	v_rcp_f32_e32 v6, v6
	v_rcp_f32_e32 v2, v2
	v_exp_f32_e32 v21, v21
	v_mul_f32_e32 v8, v8, v3
	v_mul_f32_e32 v9, v9, v6
	v_mul_f32_e32 v3, 0xbfb8aa3b, v27
	v_mul_f32_e32 v6, 0xbfb8aa3b, v28
	v_exp_f32_e32 v3, v3
	v_exp_f32_e32 v6, v6
	v_mul_f32_e32 v22, v7, v2
	v_add_f32_e32 v2, 1.0, v21
	v_add_f32_e32 v3, 1.0, v3
	v_add_f32_e32 v6, 1.0, v6
	v_mul_f32_e32 v7, 0xbfb8aa3b, v29
	v_rcp_f32_e32 v2, v2
	v_rcp_f32_e32 v3, v3
	v_rcp_f32_e32 v6, v6
	v_exp_f32_e32 v7, v7
	v_mul_f32_e32 v10, v10, v2
	v_mul_f32_e32 v11, v11, v3
	v_mul_f32_e32 v12, v12, v6
	v_add_f32_e32 v2, 1.0, v7
	v_mul_f32_e32 v3, 0xbfb8aa3b, v30
	v_mul_f32_e32 v6, 0xbfb8aa3b, v31
	v_rcp_f32_e32 v2, v2
	v_exp_f32_e32 v3, v3
	v_exp_f32_e32 v6, v6
	v_mul_f32_e32 v7, 0xbfb8aa3b, v33
	v_mul_f32_e32 v13, v13, v2
	v_add_f32_e32 v2, 1.0, v3
	v_add_f32_e32 v3, 1.0, v6
	v_rcp_f32_e32 v3, v3
	v_mul_f32_e32 v6, 0xbfb8aa3b, v32
	v_rcp_f32_e32 v2, v2
	v_exp_f32_e32 v6, v6
	v_exp_f32_e32 v7, v7
	v_mul_f32_e32 v15, v15, v3
	v_add_u32_e32 v3, 0xffffe040, v108
	v_lshrrev_b32_e32 v3, 12, v3
	v_add_f32_e32 v6, 1.0, v6
	v_add_f32_e32 v7, 1.0, v7
	v_mul_f32_e32 v14, v14, v2
	v_ashrrev_i32_e32 v2, 8, v34
	v_add_u32_e32 v3, 32, v3
	v_rcp_f32_e32 v6, v6
	v_rcp_f32_e32 v7, v7
	v_cndmask_b32_e32 v2, v3, v2, vcc
	v_lshlrev_b32_e32 v2, 5, v2
	v_add3_u32 v2, v36, v2, 16
	v_ashrrev_i32_e32 v3, 31, v2
	v_mul_f32_e32 v16, v16, v6
	v_mul_f32_e32 v17, v17, v7
	v_permlane32_swap_b32_e32 v18, v10
	v_permlane32_swap_b32_e32 v19, v11
	v_permlane32_swap_b32_e32 v4, v12
	v_permlane32_swap_b32_e32 v5, v13
	v_lshlrev_b64 v[2:3], 10, v[2:3]
	v_permlane32_swap_b32_e32 v20, v14
	v_permlane32_swap_b32_e32 v22, v15
	v_permlane32_swap_b32_e32 v8, v16
	v_permlane32_swap_b32_e32 v9, v17
	v_lshl_add_u64 v[6:7], v[116:117], 0, v[2:3]
	v_cvt_pk_bf16_f32 v2, v18, v19
	v_cvt_pk_bf16_f32 v3, v4, v5
	v_cvt_pk_bf16_f32 v4, v10, v11
	v_cvt_pk_bf16_f32 v5, v12, v13
	ds_write_b128 v203, v[2:5]
	s_nop 1
	v_cvt_pk_bf16_f32 v2, v20, v22
	v_cvt_pk_bf16_f32 v3, v8, v9
	v_cvt_pk_bf16_f32 v4, v14, v15
	v_cvt_pk_bf16_f32 v5, v16, v17
	ds_write_b128 v203, v[2:5] offset:16
	v_lshl_add_u64 v[192:193], v[6:7], 0, v[210:211]
	ds_read_b128 v[176:179], v205
	ds_read_b128 v[180:183], v205 offset:144
	s_waitcnt lgkmcnt(1)
	global_store_dwordx4 v[192:193], v[176:179], off
	s_waitcnt lgkmcnt(0)
	global_store_dwordx4 v[192:193], v[180:183], off offset:1024
	s_branch .LBB0_204
